# GEMM K-loops: lgkmcnt(0) for the fragment reads hoisted in front of the pre-MMA barrier (MFMA segment starts immediately on release)
# baseline (speedup 1.0000x reference)
; #define PG8_STAGE(bufoff, gbase, voff) do { _Pragma("unroll") for (int _i = 0; _i < 2; ++_i) \
;         __builtin_amdgcn_global_load_lds((const unsigned*)((const char*)(gbase) + (voff)[_i]), (LAS unsigned*)(lds + (bufoff) + ldsw + _i * 8192), 16, 0, 0); } while (0)
; #define PG8_LDA(dst, b, h) do { _Pragma("unroll") for (int m = 0; m < 4; ++m) _Pragma("unroll") for (int k = 0; k < 2; ++k) dst[m][k] = *(const LAS bf16x8*)(lds + PG8_SA(b, h) + aoff + m * 2048 + k * 1024); } while (0)
; #define PG8_LDB(dst, b, h) do { _Pragma("unroll") for (int n = 0; n < 2; ++n) _Pragma("unroll") for (int k = 0; k < 2; ++k) dst[n][k] = *(const LAS bf16x8*)(lds + PG8_SB(b, h) + boff + n * 2048 + k * 1024); } while (0)
; #define PG8_MMA(ai, bj, At, Bt) do { __builtin_amdgcn_s_setprio(1); _Pragma("unroll") for (int m = 0; m < 4; ++m) _Pragma("unroll") for (int n = 0; n < 2; ++n) _Pragma("unroll") for (int k = 0; k < 2; ++k) \
;         acc[ai][bj][m][n] = __builtin_amdgcn_mfma_f32_16x16x32_bf16(Bt[n][k], At[m][k], acc[ai][bj][m][n], 0, 0, 0); __builtin_amdgcn_s_setprio(0); } while (0)
; #define PG8_WAIT_V(n) asm volatile("s_waitcnt vmcnt(" #n ")" ::: "memory")
; #define PG8_WAIT_L(n) asm volatile("s_waitcnt lgkmcnt(" #n ")" ::: "memory")
; template <class Epi, class Sched, int LD>
; __device__ __forceinline__ void gemm_phase(LAS unsigned char* lds, const Gemm g, const Sched& S, const Epi& E) {
;     ...
;         for (int t = 0; t < nt; t += 2) {
;             const bool last = (t == nt - 2);
;             const char* a1 = cA + (size_t)(t + 1) * kstep;
;             const char* a2 = last ? nA : cA + (size_t)(t + 2) * kstep; const char* b2 = last ? nB : cB + (size_t)(t + 2) * kstep;
;             const char* a3 = a2 + kstep; const char* b3 = b2 + kstep;
;             PG8_LDB(B0, 0, 0); PG8_SCHED; PG8_LDA(At, 0, 0); PG8_STAGE(PG8_SA(1, 1), a1 + hstep, voffA);
;             PG8_WAIT_L(8); PG8_BAR; PG8_WAIT_L(0); PG8_MMA(0, 0, At, B0); PG8_BAR; PG8_SCHED;
;             PG8_LDB(B1, 0, 1); PG8_STAGE(PG8_SB(0, 0), b2, voffB);
;             PG8_BAR; PG8_WAIT_L(0); PG8_MMA(0, 1, At, B1); PG8_BAR;
;             PG8_LDA(At, 0, 1); PG8_STAGE(PG8_SA(0, 0), a2, voffA);
;             PG8_BAR; PG8_WAIT_L(0); PG8_MMA(1, 0, At, B0); PG8_BAR; PG8_SCHED;
;             PG8_STAGE(PG8_SB(0, 1), b2 + hstep, voffB);
;             PG8_WAIT_V(6); PG8_BAR; PG8_MMA(1, 1, At, B1); PG8_BAR;
.LBB0_58:
	s_add_i32 s71, s4, 2
	s_add_u32 s48, s46, 0x4000
	s_addc_u32 s5, s47, 0
	s_cmp_eq_u32 s68, s4
	s_cselect_b32 s4, s42, s48
	s_cselect_b32 s5, s43, s5
	s_cselect_b32 s48, s44, s69
	s_cselect_b32 s49, s45, s70
	s_add_u32 s50, s4, 0x8000
	s_addc_u32 s51, s5, 0
	s_add_i32 s72, 0, 0x10000
	s_add_i32 m0, s39, 0xc000
	ds_read_b128 v[180:183], v148
	ds_read_b128 v[184:187], v148 offset:1024
	ds_read_b128 v[188:191], v148 offset:2048
	ds_read_b128 v[192:195], v148 offset:3072
	ds_read_b128 v[196:199], v148 offset:4096
	ds_read_b128 v[200:203], v148 offset:5120
	ds_read_b128 v[204:207], v148 offset:6144
	ds_read_b128 v[208:211], v148 offset:7168
	global_load_lds_dwordx4 v132, s[46:47]
	s_add_i32 m0, s39, 0xe000
	s_nop 0
	global_load_lds_dwordx4 v138, s[46:47]
	s_waitcnt lgkmcnt(8)
	s_waitcnt lgkmcnt(0)
	s_barrier
	s_setprio 0
	v_mfma_f32_16x16x32_bf16 v[128:131], v[140:143], v[180:183], v[128:131]
	v_mfma_f32_16x16x32_bf16 v[124:127], v[154:157], v[180:183], v[124:127]
	v_mfma_f32_16x16x32_bf16 v[112:115], v[140:143], v[188:191], v[112:115]
	v_mfma_f32_16x16x32_bf16 v[108:111], v[154:157], v[188:191], v[108:111]
	v_mfma_f32_16x16x32_bf16 v[96:99], v[140:143], v[196:199], v[96:99]
	v_mfma_f32_16x16x32_bf16 v[92:95], v[154:157], v[196:199], v[92:95]
	v_mfma_f32_16x16x32_bf16 v[80:83], v[140:143], v[204:207], v[80:83]
	v_mfma_f32_16x16x32_bf16 v[76:79], v[154:157], v[204:207], v[76:79]
	v_mfma_f32_16x16x32_bf16 v[128:131], v[150:153], v[184:187], v[128:131]
	v_mfma_f32_16x16x32_bf16 v[124:127], v[176:179], v[184:187], v[124:127]
	v_mfma_f32_16x16x32_bf16 v[112:115], v[150:153], v[192:195], v[112:115]
	v_mfma_f32_16x16x32_bf16 v[108:111], v[176:179], v[192:195], v[108:111]
	v_mfma_f32_16x16x32_bf16 v[96:99], v[150:153], v[200:203], v[96:99]
	v_mfma_f32_16x16x32_bf16 v[92:95], v[176:179], v[200:203], v[92:95]
	s_setprio 3
	s_barrier
	v_mfma_f32_16x16x32_bf16 v[80:83], v[150:153], v[208:211], v[80:83]
	v_mfma_f32_16x16x32_bf16 v[76:79], v[176:179], v[208:211], v[76:79]
	s_setprio 2
	s_add_i32 s74, 0, 0x14000
	s_add_i32 s72, s72, s29
	ds_read_b128 v[212:215], v228 offset:16384
	ds_read_b128 v[216:219], v228 offset:17408
	ds_read_b128 v[220:223], v228 offset:18432
	ds_read_b128 v[224:227], v228 offset:19456
	s_mov_b32 m0, s72
	s_nop 0
	global_load_lds_dwordx4 v132, s[48:49]
	s_add_i32 m0, s72, 0x2000
	s_nop 0
	global_load_lds_dwordx4 v138, s[48:49]
	s_waitcnt lgkmcnt(0)
	s_barrier
	s_setprio 0
	v_mfma_f32_16x16x32_bf16 v[120:123], v[212:215], v[180:183], v[120:123]
	v_mfma_f32_16x16x32_bf16 v[116:119], v[220:223], v[180:183], v[116:119]
	v_mfma_f32_16x16x32_bf16 v[104:107], v[212:215], v[188:191], v[104:107]
	v_mfma_f32_16x16x32_bf16 v[100:103], v[220:223], v[188:191], v[100:103]
	v_mfma_f32_16x16x32_bf16 v[88:91], v[212:215], v[196:199], v[88:91]
	v_mfma_f32_16x16x32_bf16 v[84:87], v[220:223], v[196:199], v[84:87]
	v_mfma_f32_16x16x32_bf16 v[72:75], v[212:215], v[204:207], v[72:75]
	v_mfma_f32_16x16x32_bf16 v[68:71], v[220:223], v[204:207], v[68:71]
	v_mfma_f32_16x16x32_bf16 v[120:123], v[216:219], v[184:187], v[120:123]
	v_mfma_f32_16x16x32_bf16 v[116:119], v[224:227], v[184:187], v[116:119]
	v_mfma_f32_16x16x32_bf16 v[104:107], v[216:219], v[192:195], v[104:107]
	v_mfma_f32_16x16x32_bf16 v[100:103], v[224:227], v[192:195], v[100:103]
	v_mfma_f32_16x16x32_bf16 v[88:91], v[216:219], v[200:203], v[88:91]
	v_mfma_f32_16x16x32_bf16 v[84:87], v[224:227], v[200:203], v[84:87]
	v_mfma_f32_16x16x32_bf16 v[72:75], v[216:219], v[208:211], v[72:75]
	v_mfma_f32_16x16x32_bf16 v[68:71], v[224:227], v[208:211], v[68:71]
	s_setprio 2
	s_mov_b32 m0, s39
	s_barrier
	ds_read_b128 v[180:183], v148 offset:16384
	ds_read_b128 v[184:187], v148 offset:17408
	ds_read_b128 v[188:191], v148 offset:18432
	ds_read_b128 v[192:195], v148 offset:19456
	ds_read_b128 v[196:199], v148 offset:20480
	ds_read_b128 v[200:203], v148 offset:21504
	ds_read_b128 v[204:207], v148 offset:22528
	ds_read_b128 v[208:211], v148 offset:23552
	global_load_lds_dwordx4 v132, s[4:5]
	s_mov_b32 m0, s52
	s_nop 0
	global_load_lds_dwordx4 v138, s[4:5]
	s_waitcnt vmcnt(10)
	s_waitcnt lgkmcnt(0)
	s_barrier
	s_setprio 0
	v_mfma_f32_16x16x32_bf16 v[64:67], v[140:143], v[180:183], v[64:67]
	v_mfma_f32_16x16x32_bf16 v[60:63], v[154:157], v[180:183], v[60:63]
	v_mfma_f32_16x16x32_bf16 v[48:51], v[140:143], v[188:191], v[48:51]
	v_mfma_f32_16x16x32_bf16 v[44:47], v[154:157], v[188:191], v[44:47]
	v_mfma_f32_16x16x32_bf16 v[32:35], v[140:143], v[196:199], v[32:35]
	v_mfma_f32_16x16x32_bf16 v[28:31], v[154:157], v[196:199], v[28:31]
	v_mfma_f32_16x16x32_bf16 v[16:19], v[140:143], v[204:207], v[16:19]
	v_mfma_f32_16x16x32_bf16 v[12:15], v[154:157], v[204:207], v[12:15]
	v_mfma_f32_16x16x32_bf16 v[64:67], v[150:153], v[184:187], v[64:67]
	v_mfma_f32_16x16x32_bf16 v[60:63], v[176:179], v[184:187], v[60:63]
	v_mfma_f32_16x16x32_bf16 v[48:51], v[150:153], v[192:195], v[48:51]
	v_mfma_f32_16x16x32_bf16 v[44:47], v[176:179], v[192:195], v[44:47]
	v_mfma_f32_16x16x32_bf16 v[32:35], v[150:153], v[200:203], v[32:35]
	v_mfma_f32_16x16x32_bf16 v[28:31], v[176:179], v[200:203], v[28:31]
	s_setprio 3
	s_barrier
	v_mfma_f32_16x16x32_bf16 v[16:19], v[150:153], v[208:211], v[16:19]
	v_mfma_f32_16x16x32_bf16 v[12:15], v[176:179], v[208:211], v[12:15]
	s_setprio 2
	ds_read_b128 v[140:143], v228 offset:32768
	ds_read_b128 v[150:153], v228 offset:33792
	ds_read_b128 v[154:157], v228 offset:34816
	ds_read_b128 v[176:179], v228 offset:35840
	s_add_u32 s72, s48, 0x4000
	s_addc_u32 s73, s49, 0
	s_add_i32 s74, s74, s29
	s_mov_b32 m0, s74
	s_nop 0
	global_load_lds_dwordx4 v132, s[72:73]
	s_add_i32 m0, s74, 0x2000
	s_nop 0
	global_load_lds_dwordx4 v138, s[72:73]
	s_waitcnt vmcnt(6)
	s_barrier
; #define PG8_STAGE(bufoff, gbase, voff) do { _Pragma("unroll") for (int _i = 0; _i < 2; ++_i) \
;         __builtin_amdgcn_global_load_lds((const unsigned*)((const char*)(gbase) + (voff)[_i]), (LAS unsigned*)(lds + (bufoff) + ldsw + _i * 8192), 16, 0, 0); } while (0)
; #define PG8_LDA(dst, b, h) do { _Pragma("unroll") for (int m = 0; m < 4; ++m) _Pragma("unroll") for (int k = 0; k < 2; ++k) dst[m][k] = *(const LAS bf16x8*)(lds + PG8_SA(b, h) + aoff + m * 2048 + k * 1024); } while (0)
; #define PG8_LDB(dst, b, h) do { _Pragma("unroll") for (int n = 0; n < 2; ++n) _Pragma("unroll") for (int k = 0; k < 2; ++k) dst[n][k] = *(const LAS bf16x8*)(lds + PG8_SB(b, h) + boff + n * 2048 + k * 1024); } while (0)
; #define PG8_MMA(ai, bj, At, Bt) do { __builtin_amdgcn_s_setprio(1); _Pragma("unroll") for (int m = 0; m < 4; ++m) _Pragma("unroll") for (int n = 0; n < 2; ++n) _Pragma("unroll") for (int k = 0; k < 2; ++k) \
;         acc[ai][bj][m][n] = __builtin_amdgcn_mfma_f32_16x16x32_bf16(Bt[n][k], At[m][k], acc[ai][bj][m][n], 0, 0, 0); __builtin_amdgcn_s_setprio(0); } while (0)
; #define PG8_WAIT_V(n) asm volatile("s_waitcnt vmcnt(" #n ")" ::: "memory")
; #define PG8_WAIT_L(n) asm volatile("s_waitcnt lgkmcnt(" #n ")" ::: "memory")
; #define PG8_BAR __builtin_amdgcn_s_barrier()
; #define PG8_SCHED __builtin_amdgcn_sched_barrier(0)
; template <class Epi, class Sched, int LD>
; __device__ __forceinline__ void gemm_phase(LAS unsigned char* lds, const Gemm g, const Sched& S, const Epi& E) {
;     ...
;             PG8_WAIT_V(6); PG8_BAR; PG8_MMA(1, 1, At, B1); PG8_BAR;
;             PG8_LDB(B0, 1, 0); PG8_SCHED; PG8_LDA(At, 1, 0); PG8_STAGE(PG8_SA(0, 1), a2 + hstep, voffA);
;             PG8_WAIT_L(8); PG8_BAR; PG8_WAIT_L(0); PG8_MMA(0, 0, At, B0); PG8_BAR; PG8_SCHED;
;             PG8_LDB(B1, 1, 1); PG8_STAGE(PG8_SB(1, 0), b3, voffB);
;             PG8_BAR; PG8_WAIT_L(0); PG8_MMA(0, 1, At, B1); PG8_BAR;
;             PG8_LDA(At, 1, 1); PG8_STAGE(PG8_SA(1, 0), a3, voffA);
;             PG8_BAR; PG8_WAIT_L(0); PG8_MMA(1, 0, At, B0); PG8_BAR; PG8_SCHED;
	s_setprio 0
	v_mfma_f32_16x16x32_bf16 v[56:59], v[212:215], v[180:183], v[56:59]
	v_mfma_f32_16x16x32_bf16 v[52:55], v[220:223], v[180:183], v[52:55]
	v_mfma_f32_16x16x32_bf16 v[40:43], v[212:215], v[188:191], v[40:43]
	v_mfma_f32_16x16x32_bf16 v[36:39], v[220:223], v[188:191], v[36:39]
	v_mfma_f32_16x16x32_bf16 v[24:27], v[212:215], v[196:199], v[24:27]
	v_mfma_f32_16x16x32_bf16 v[20:23], v[220:223], v[196:199], v[20:23]
	v_mfma_f32_16x16x32_bf16 v[8:11], v[212:215], v[204:207], v[8:11]
	v_mfma_f32_16x16x32_bf16 v[4:7], v[220:223], v[204:207], v[4:7]
	v_mfma_f32_16x16x32_bf16 v[56:59], v[216:219], v[184:187], v[56:59]
	v_mfma_f32_16x16x32_bf16 v[52:55], v[224:227], v[184:187], v[52:55]
	v_mfma_f32_16x16x32_bf16 v[40:43], v[216:219], v[192:195], v[40:43]
	v_mfma_f32_16x16x32_bf16 v[36:39], v[224:227], v[192:195], v[36:39]
	v_mfma_f32_16x16x32_bf16 v[24:27], v[216:219], v[200:203], v[24:27]
	v_mfma_f32_16x16x32_bf16 v[20:23], v[224:227], v[200:203], v[20:23]
	v_mfma_f32_16x16x32_bf16 v[8:11], v[216:219], v[208:211], v[8:11]
	v_mfma_f32_16x16x32_bf16 v[4:7], v[224:227], v[208:211], v[4:7]
	s_setprio 2
	s_add_i32 s72, 0, 0x18000
	s_barrier
	s_add_u32 s4, s4, 0x4000
	s_addc_u32 s5, s5, 0
	s_mov_b32 m0, s53
	ds_read_b128 v[180:183], v148 offset:32768
	ds_read_b128 v[184:187], v148 offset:33792
	ds_read_b128 v[188:191], v148 offset:34816
	ds_read_b128 v[192:195], v148 offset:35840
	ds_read_b128 v[196:199], v148 offset:36864
	ds_read_b128 v[200:203], v148 offset:37888
	ds_read_b128 v[204:207], v148 offset:38912
	ds_read_b128 v[208:211], v148 offset:39936
	global_load_lds_dwordx4 v132, s[4:5]
	s_mov_b32 m0, s54
	s_nop 0
	global_load_lds_dwordx4 v138, s[4:5]
	s_waitcnt lgkmcnt(8)
	s_waitcnt lgkmcnt(0)
	s_barrier
	s_setprio 0
	v_mfma_f32_16x16x32_bf16 v[128:131], v[140:143], v[180:183], v[128:131]
	v_mfma_f32_16x16x32_bf16 v[124:127], v[154:157], v[180:183], v[124:127]
	v_mfma_f32_16x16x32_bf16 v[112:115], v[140:143], v[188:191], v[112:115]
	v_mfma_f32_16x16x32_bf16 v[108:111], v[154:157], v[188:191], v[108:111]
	v_mfma_f32_16x16x32_bf16 v[96:99], v[140:143], v[196:199], v[96:99]
	v_mfma_f32_16x16x32_bf16 v[92:95], v[154:157], v[196:199], v[92:95]
	v_mfma_f32_16x16x32_bf16 v[80:83], v[140:143], v[204:207], v[80:83]
	v_mfma_f32_16x16x32_bf16 v[76:79], v[154:157], v[204:207], v[76:79]
	v_mfma_f32_16x16x32_bf16 v[128:131], v[150:153], v[184:187], v[128:131]
	v_mfma_f32_16x16x32_bf16 v[124:127], v[176:179], v[184:187], v[124:127]
	v_mfma_f32_16x16x32_bf16 v[112:115], v[150:153], v[192:195], v[112:115]
	v_mfma_f32_16x16x32_bf16 v[108:111], v[176:179], v[192:195], v[108:111]
	v_mfma_f32_16x16x32_bf16 v[96:99], v[150:153], v[200:203], v[96:99]
	v_mfma_f32_16x16x32_bf16 v[92:95], v[176:179], v[200:203], v[92:95]
	s_setprio 3
	s_barrier
	v_mfma_f32_16x16x32_bf16 v[80:83], v[150:153], v[208:211], v[80:83]
	v_mfma_f32_16x16x32_bf16 v[76:79], v[176:179], v[208:211], v[76:79]
	s_setprio 2
	s_add_i32 s73, 0, 0x1c000
	s_add_u32 s4, s48, 0x8000
	s_addc_u32 s5, s49, 0
	s_add_i32 s72, s72, s29
	ds_read_b128 v[212:215], v228 offset:49152
	ds_read_b128 v[216:219], v228 offset:50176
	ds_read_b128 v[220:223], v228 offset:51200
	ds_read_b128 v[224:227], v228 offset:52224
	s_mov_b32 m0, s72
	s_nop 0
	global_load_lds_dwordx4 v132, s[4:5]
	s_add_i32 m0, s72, 0x2000
	s_nop 0
	global_load_lds_dwordx4 v138, s[4:5]
	s_waitcnt lgkmcnt(0)
	s_barrier
	s_setprio 0
	v_mfma_f32_16x16x32_bf16 v[120:123], v[212:215], v[180:183], v[120:123]
	v_mfma_f32_16x16x32_bf16 v[116:119], v[220:223], v[180:183], v[116:119]
	v_mfma_f32_16x16x32_bf16 v[104:107], v[212:215], v[188:191], v[104:107]
	v_mfma_f32_16x16x32_bf16 v[100:103], v[220:223], v[188:191], v[100:103]
	v_mfma_f32_16x16x32_bf16 v[88:91], v[212:215], v[196:199], v[88:91]
	v_mfma_f32_16x16x32_bf16 v[84:87], v[220:223], v[196:199], v[84:87]
	v_mfma_f32_16x16x32_bf16 v[72:75], v[212:215], v[204:207], v[72:75]
	v_mfma_f32_16x16x32_bf16 v[68:71], v[220:223], v[204:207], v[68:71]
	v_mfma_f32_16x16x32_bf16 v[120:123], v[216:219], v[184:187], v[120:123]
	v_mfma_f32_16x16x32_bf16 v[116:119], v[224:227], v[184:187], v[116:119]
	v_mfma_f32_16x16x32_bf16 v[104:107], v[216:219], v[192:195], v[104:107]
	v_mfma_f32_16x16x32_bf16 v[100:103], v[224:227], v[192:195], v[100:103]
	v_mfma_f32_16x16x32_bf16 v[88:91], v[216:219], v[200:203], v[88:91]
	v_mfma_f32_16x16x32_bf16 v[84:87], v[224:227], v[200:203], v[84:87]
	v_mfma_f32_16x16x32_bf16 v[72:75], v[216:219], v[208:211], v[72:75]
	v_mfma_f32_16x16x32_bf16 v[68:71], v[224:227], v[208:211], v[68:71]
	s_setprio 2
	s_mov_b32 m0, s55
	s_barrier
	ds_read_b128 v[180:183], v148 offset:49152
	ds_read_b128 v[184:187], v148 offset:50176
	ds_read_b128 v[188:191], v148 offset:51200
	ds_read_b128 v[192:195], v148 offset:52224
	ds_read_b128 v[196:199], v148 offset:53248
	ds_read_b128 v[200:203], v148 offset:54272
	ds_read_b128 v[204:207], v148 offset:55296
	ds_read_b128 v[208:211], v148 offset:56320
	global_load_lds_dwordx4 v132, s[50:51]
	s_mov_b32 m0, s56
	s_nop 0
	global_load_lds_dwordx4 v138, s[50:51]
	s_waitcnt vmcnt(10)
	s_waitcnt lgkmcnt(0)
	s_barrier
	s_setprio 0
	v_mfma_f32_16x16x32_bf16 v[64:67], v[140:143], v[180:183], v[64:67]
	v_mfma_f32_16x16x32_bf16 v[60:63], v[154:157], v[180:183], v[60:63]
	v_mfma_f32_16x16x32_bf16 v[48:51], v[140:143], v[188:191], v[48:51]
	v_mfma_f32_16x16x32_bf16 v[44:47], v[154:157], v[188:191], v[44:47]
	v_mfma_f32_16x16x32_bf16 v[32:35], v[140:143], v[196:199], v[32:35]
	v_mfma_f32_16x16x32_bf16 v[28:31], v[154:157], v[196:199], v[28:31]
	v_mfma_f32_16x16x32_bf16 v[16:19], v[140:143], v[204:207], v[16:19]
	v_mfma_f32_16x16x32_bf16 v[12:15], v[154:157], v[204:207], v[12:15]
	v_mfma_f32_16x16x32_bf16 v[64:67], v[150:153], v[184:187], v[64:67]
	v_mfma_f32_16x16x32_bf16 v[60:63], v[176:179], v[184:187], v[60:63]
	v_mfma_f32_16x16x32_bf16 v[48:51], v[150:153], v[192:195], v[48:51]
	v_mfma_f32_16x16x32_bf16 v[44:47], v[176:179], v[192:195], v[44:47]
	v_mfma_f32_16x16x32_bf16 v[32:35], v[150:153], v[200:203], v[32:35]
	v_mfma_f32_16x16x32_bf16 v[28:31], v[176:179], v[200:203], v[28:31]
	s_setprio 3
	s_barrier
; #define PG8_STAGE(bufoff, gbase, voff) do { _Pragma("unroll") for (int _i = 0; _i < 2; ++_i) \
;         __builtin_amdgcn_global_load_lds((const unsigned*)((const char*)(gbase) + (voff)[_i]), (LAS unsigned*)(lds + (bufoff) + ldsw + _i * 8192), 16, 0, 0); } while (0)
; #define PG8_MMA(ai, bj, At, Bt) do { __builtin_amdgcn_s_setprio(1); _Pragma("unroll") for (int m = 0; m < 4; ++m) _Pragma("unroll") for (int n = 0; n < 2; ++n) _Pragma("unroll") for (int k = 0; k < 2; ++k) \
;         acc[ai][bj][m][n] = __builtin_amdgcn_mfma_f32_16x16x32_bf16(Bt[n][k], At[m][k], acc[ai][bj][m][n], 0, 0, 0); __builtin_amdgcn_s_setprio(0); } while (0)
; #define PG8_WAIT_V(n) asm volatile("s_waitcnt vmcnt(" #n ")" ::: "memory")
; #define PG8_WAIT_L(n) asm volatile("s_waitcnt lgkmcnt(" #n ")" ::: "memory")
; #define PG8_BAR __builtin_amdgcn_s_barrier()
; #define PG8_SCHED __builtin_amdgcn_sched_barrier(0)
;     __device__ __forceinline__ void operator()(const f32x4 (&acc)[2][2][4][2], const Unit& u, int wr, int wc, int fr, int fq) const {
;     ...
;         } else {
;             float* base = PART + (size_t)u.part * (512 * 2048);
; #pragma unroll
;             for (int ai = 0; ai < 2; ++ai)
; #pragma unroll
;                 for (int m = 0; m < 4; ++m) {
;                     float* rowp = base + (size_t)(row0 - 8192 + ai * HALF + m * 16) * D_MODEL + col0;
; #pragma unroll
;                     for (int bj = 0; bj < 2; ++bj)
; #pragma unroll
;                         for (int n = 0; n < 2; ++n) *(f32x4*)(rowp + bj * HALF + n * 16) = acc[ai][bj][m][n];
;                 }
;         }
; template <class Epi, class Sched, int LD>
; __device__ __forceinline__ void gemm_phase(LAS unsigned char* lds, const Gemm g, const Sched& S, const Epi& E) {
;     ...
;             PG8_BAR; PG8_WAIT_L(0); PG8_MMA(1, 0, At, B0); PG8_BAR; PG8_SCHED;
;             PG8_STAGE(PG8_SB(1, 1), b3 + hstep, voffB);
;             PG8_WAIT_V(6); PG8_BAR; PG8_MMA(1, 1, At, B1); PG8_BAR;
	v_mfma_f32_16x16x32_bf16 v[16:19], v[150:153], v[208:211], v[16:19]
	v_mfma_f32_16x16x32_bf16 v[12:15], v[176:179], v[208:211], v[12:15]
	s_setprio 2
	ds_read_b128 v[140:143], v228
	ds_read_b128 v[150:153], v228 offset:1024
	ds_read_b128 v[154:157], v228 offset:2048
	ds_read_b128 v[176:179], v228 offset:3072
	s_add_u32 s4, s48, 0xc000
	s_addc_u32 s5, s49, 0
	s_add_i32 s48, s73, s29
	s_mov_b32 m0, s48
	s_nop 0
	global_load_lds_dwordx4 v132, s[4:5]
	s_add_i32 m0, s48, 0x2000
	s_nop 0
	global_load_lds_dwordx4 v138, s[4:5]
	s_waitcnt vmcnt(6)
	s_barrier
	s_setprio 0
	v_mfma_f32_16x16x32_bf16 v[56:59], v[212:215], v[180:183], v[56:59]
	v_mfma_f32_16x16x32_bf16 v[52:55], v[220:223], v[180:183], v[52:55]
	v_mfma_f32_16x16x32_bf16 v[40:43], v[212:215], v[188:191], v[40:43]
	v_mfma_f32_16x16x32_bf16 v[36:39], v[220:223], v[188:191], v[36:39]
	v_mfma_f32_16x16x32_bf16 v[24:27], v[212:215], v[196:199], v[24:27]
	v_mfma_f32_16x16x32_bf16 v[20:23], v[220:223], v[196:199], v[20:23]
	v_mfma_f32_16x16x32_bf16 v[8:11], v[212:215], v[204:207], v[8:11]
	v_mfma_f32_16x16x32_bf16 v[4:7], v[220:223], v[204:207], v[4:7]
	v_mfma_f32_16x16x32_bf16 v[56:59], v[216:219], v[184:187], v[56:59]
	v_mfma_f32_16x16x32_bf16 v[52:55], v[224:227], v[184:187], v[52:55]
	v_mfma_f32_16x16x32_bf16 v[40:43], v[216:219], v[192:195], v[40:43]
	v_mfma_f32_16x16x32_bf16 v[36:39], v[224:227], v[192:195], v[36:39]
	v_mfma_f32_16x16x32_bf16 v[24:27], v[216:219], v[200:203], v[24:27]
	v_mfma_f32_16x16x32_bf16 v[20:23], v[224:227], v[200:203], v[20:23]
	v_mfma_f32_16x16x32_bf16 v[8:11], v[216:219], v[208:211], v[8:11]
	v_mfma_f32_16x16x32_bf16 v[4:7], v[224:227], v[208:211], v[4:7]
	s_setprio 2
	s_add_u32 s46, s46, 0x10000
	s_addc_u32 s47, s47, 0
	s_add_u32 s69, s69, 0x10000
	s_addc_u32 s70, s70, 0
	s_cmp_ge_i32 s71, s65
	s_mov_b32 s4, s71
	s_barrier
	s_cbranch_scc0 .LBB0_58
	s_setprio 0
	v_lshl_add_u32 v142, s67, 8, v137
	v_lshl_or_b32 v140, s66, 8, v147
	s_mov_b64 s[4:5], -1
	s_cmp_gt_i32 s18, -1
	v_ashrrev_i32_e32 v141, 31, v140
	v_ashrrev_i32_e32 v143, 31, v142
	s_cbranch_scc0 .LBB0_61
	s_lshl_b64 s[4:5], s[18:19], 22
	v_readlane_b32 s18, v252, 10
	s_add_u32 s4, s18, s4
	v_readlane_b32 s18, v252, 11
	s_addc_u32 s5, s18, s5
	v_lshl_add_u64 v[144:145], v[140:141], 2, s[4:5]
	v_lshlrev_b64 v[150:151], 13, v[142:143]
	s_brev_b32 s4, 63
	v_lshl_add_u64 v[144:145], v[144:145], 0, v[150:151]
	s_mov_b32 s5, -1
	v_lshl_add_u64 v[150:151], v[144:145], 0, s[4:5]
	s_brev_b32 s4, 63
	v_add_co_u32_e32 v152, vcc, s4, v144
	s_mov_b32 s4, 0xfc020000
	s_nop 0
	v_addc_co_u32_e32 v153, vcc, -1, v145, vcc
	s_mov_b32 s5, -1
	global_store_dwordx4 v[152:153], v[128:131], off
	global_store_dwordx4 v[150:151], v[124:127], off offset:64
	global_store_dwordx4 v[150:151], v[120:123], off offset:512
	global_store_dwordx4 v[150:151], v[116:119], off offset:576
	v_lshl_add_u64 v[150:151], v[144:145], 0, s[4:5]
	s_mov_b32 s4, 0xfc020000
	v_add_co_u32_e32 v152, vcc, s4, v144
	s_mov_b32 s4, 0xfc040000
	s_nop 0
	v_addc_co_u32_e32 v153, vcc, -1, v145, vcc
	s_mov_b32 s5, -1
	global_store_dwordx4 v[152:153], v[112:115], off
	global_store_dwordx4 v[150:151], v[108:111], off offset:64
	global_store_dwordx4 v[150:151], v[104:107], off offset:512
	global_store_dwordx4 v[150:151], v[100:103], off offset:576
	v_lshl_add_u64 v[150:151], v[144:145], 0, s[4:5]
	s_mov_b32 s4, 0xfc040000
	v_add_co_u32_e32 v152, vcc, s4, v144
	s_mov_b32 s4, 0xfc060000
	s_nop 0
	v_addc_co_u32_e32 v153, vcc, -1, v145, vcc
	s_mov_b32 s5, -1
	global_store_dwordx4 v[152:153], v[96:99], off
	global_store_dwordx4 v[150:151], v[92:95], off offset:64
	global_store_dwordx4 v[150:151], v[88:91], off offset:512
	global_store_dwordx4 v[150:151], v[84:87], off offset:576
	v_lshl_add_u64 v[150:151], v[144:145], 0, s[4:5]
	s_mov_b32 s4, 0xfc060000
	v_add_co_u32_e32 v152, vcc, s4, v144
	s_mov_b32 s4, 0xfc100000
	s_nop 0
	v_addc_co_u32_e32 v153, vcc, -1, v145, vcc
	s_mov_b32 s5, -1
	global_store_dwordx4 v[152:153], v[80:83], off
	global_store_dwordx4 v[150:151], v[76:79], off offset:64
	global_store_dwordx4 v[150:151], v[72:75], off offset:512
	global_store_dwordx4 v[150:151], v[68:71], off offset:576
	v_lshl_add_u64 v[150:151], v[144:145], 0, s[4:5]
	s_mov_b32 s4, 0xfc100000
	v_add_co_u32_e32 v152, vcc, s4, v144
	s_mov_b32 s4, 0xfc120000
	s_nop 0
	v_addc_co_u32_e32 v153, vcc, -1, v145, vcc
	s_mov_b32 s5, -1
	global_store_dwordx4 v[152:153], v[64:67], off
	global_store_dwordx4 v[150:151], v[60:63], off offset:64
	global_store_dwordx4 v[150:151], v[56:59], off offset:512
	global_store_dwordx4 v[150:151], v[52:55], off offset:576
	v_lshl_add_u64 v[150:151], v[144:145], 0, s[4:5]
	s_mov_b32 s4, 0xfc120000
	v_add_co_u32_e32 v152, vcc, s4, v144
	s_mov_b32 s4, 0xfc140000
	s_nop 0
	v_addc_co_u32_e32 v153, vcc, -1, v145, vcc
	s_mov_b32 s5, -1
	global_store_dwordx4 v[152:153], v[48:51], off
	global_store_dwordx4 v[150:151], v[44:47], off offset:64
	global_store_dwordx4 v[150:151], v[40:43], off offset:512
	global_store_dwordx4 v[150:151], v[36:39], off offset:576
	v_lshl_add_u64 v[150:151], v[144:145], 0, s[4:5]
	s_mov_b32 s4, 0xfc140000
	v_add_co_u32_e32 v152, vcc, s4, v144
	s_mov_b32 s4, 0xfc160000
	s_nop 0
	v_addc_co_u32_e32 v153, vcc, -1, v145, vcc
	s_mov_b32 s5, -1
	global_store_dwordx4 v[152:153], v[32:35], off
	global_store_dwordx4 v[150:151], v[28:31], off offset:64
	global_store_dwordx4 v[150:151], v[24:27], off offset:512
	global_store_dwordx4 v[150:151], v[20:23], off offset:576
	v_lshl_add_u64 v[150:151], v[144:145], 0, s[4:5]
	v_add_co_u32_e32 v144, vcc, 0xfc160000, v144
	s_mov_b64 s[4:5], 0
	s_nop 0
	v_addc_co_u32_e32 v145, vcc, -1, v145, vcc
	global_store_dwordx4 v[144:145], v[16:19], off
	global_store_dwordx4 v[150:151], v[12:15], off offset:64
	global_store_dwordx4 v[150:151], v[8:11], off offset:512
	global_store_dwordx4 v[150:151], v[4:7], off offset:576

; #define PG8_STAGE(bufoff, gbase, voff) do { _Pragma("unroll") for (int _i = 0; _i < 2; ++_i) \
;         __builtin_amdgcn_global_load_lds((const unsigned*)((const char*)(gbase) + (voff)[_i]), (LAS unsigned*)(lds + (bufoff) + ldsw + _i * 8192), 16, 0, 0); } while (0)
; #define PG8_LDA(dst, b, h) do { _Pragma("unroll") for (int m = 0; m < 4; ++m) _Pragma("unroll") for (int k = 0; k < 2; ++k) dst[m][k] = *(const LAS bf16x8*)(lds + PG8_SA(b, h) + aoff + m * 2048 + k * 1024); } while (0)
; #define PG8_LDB(dst, b, h) do { _Pragma("unroll") for (int n = 0; n < 2; ++n) _Pragma("unroll") for (int k = 0; k < 2; ++k) dst[n][k] = *(const LAS bf16x8*)(lds + PG8_SB(b, h) + boff + n * 2048 + k * 1024); } while (0)
; #define PG8_MMA(ai, bj, At, Bt) do { __builtin_amdgcn_s_setprio(1); _Pragma("unroll") for (int m = 0; m < 4; ++m) _Pragma("unroll") for (int n = 0; n < 2; ++n) _Pragma("unroll") for (int k = 0; k < 2; ++k) \
;         acc[ai][bj][m][n] = __builtin_amdgcn_mfma_f32_16x16x32_bf16(Bt[n][k], At[m][k], acc[ai][bj][m][n], 0, 0, 0); __builtin_amdgcn_s_setprio(0); } while (0)
; #define PG8_WAIT_V(n) asm volatile("s_waitcnt vmcnt(" #n ")" ::: "memory")
; #define PG8_WAIT_L(n) asm volatile("s_waitcnt lgkmcnt(" #n ")" ::: "memory")
; template <class Epi, class Sched, int LD>
; __device__ __forceinline__ void gemm_phase(LAS unsigned char* lds, const Gemm g, const Sched& S, const Epi& E) {
;     ...
;         for (int t = 0; t < nt; t += 2) {
;             const bool last = (t == nt - 2);
;             const char* a1 = cA + (size_t)(t + 1) * kstep;
;             const char* a2 = last ? nA : cA + (size_t)(t + 2) * kstep; const char* b2 = last ? nB : cB + (size_t)(t + 2) * kstep;
;             const char* a3 = a2 + kstep; const char* b3 = b2 + kstep;
;             PG8_LDB(B0, 0, 0); PG8_SCHED; PG8_LDA(At, 0, 0); PG8_STAGE(PG8_SA(1, 1), a1 + hstep, voffA);
;             PG8_WAIT_L(8); PG8_BAR; PG8_WAIT_L(0); PG8_MMA(0, 0, At, B0); PG8_BAR; PG8_SCHED;
;             PG8_LDB(B1, 0, 1); PG8_STAGE(PG8_SB(0, 0), b2, voffB);
;             PG8_BAR; PG8_WAIT_L(0); PG8_MMA(0, 1, At, B1); PG8_BAR;
;             PG8_LDA(At, 0, 1); PG8_STAGE(PG8_SA(0, 0), a2, voffA);
;             PG8_BAR; PG8_WAIT_L(0); PG8_MMA(1, 0, At, B0); PG8_BAR; PG8_SCHED;
;             PG8_STAGE(PG8_SB(0, 1), b2 + hstep, voffB);
;             PG8_WAIT_V(6); PG8_BAR; PG8_MMA(1, 1, At, B1); PG8_BAR;
.LBB0_501:
	s_add_u32 s4, s54, 0x4000
	s_addc_u32 s5, s55, 0
	s_cmp_eq_u32 s49, 28
	s_cselect_b32 s4, s50, s4
	s_cselect_b32 s5, s51, s5
	s_cselect_b32 s56, s40, s29
	s_cselect_b32 s57, s41, s47
	s_add_u32 s58, s4, 0x8000
	s_addc_u32 s59, s5, 0
	s_add_i32 s69, 0, 0x10000
	s_add_i32 m0, s52, 0xc000
	ds_read_b128 v[180:183], v146
	ds_read_b128 v[184:187], v146 offset:1024
	ds_read_b128 v[188:191], v146 offset:2048
	ds_read_b128 v[192:195], v146 offset:3072
	ds_read_b128 v[196:199], v146 offset:4096
	ds_read_b128 v[200:203], v146 offset:5120
	ds_read_b128 v[204:207], v146 offset:6144
	ds_read_b128 v[208:211], v146 offset:7168
	global_load_lds_dwordx4 v132, s[54:55]
	s_add_i32 m0, s52, 0xe000
	s_nop 0
	global_load_lds_dwordx4 v138, s[54:55]
	s_waitcnt lgkmcnt(8)
	s_waitcnt lgkmcnt(0)
	s_barrier
	s_setprio 0
	v_mfma_f32_16x16x32_bf16 v[128:131], v[148:151], v[180:183], v[128:131]
	v_mfma_f32_16x16x32_bf16 v[124:127], v[156:159], v[180:183], v[124:127]
	v_mfma_f32_16x16x32_bf16 v[120:123], v[148:151], v[188:191], v[120:123]
	v_mfma_f32_16x16x32_bf16 v[116:119], v[156:159], v[188:191], v[116:119]
	v_mfma_f32_16x16x32_bf16 v[104:107], v[148:151], v[196:199], v[104:107]
	v_mfma_f32_16x16x32_bf16 v[100:103], v[156:159], v[196:199], v[100:103]
	v_mfma_f32_16x16x32_bf16 v[88:91], v[148:151], v[204:207], v[88:91]
	v_mfma_f32_16x16x32_bf16 v[84:87], v[156:159], v[204:207], v[84:87]
	v_mfma_f32_16x16x32_bf16 v[128:131], v[152:155], v[184:187], v[128:131]
	v_mfma_f32_16x16x32_bf16 v[124:127], v[176:179], v[184:187], v[124:127]
	v_mfma_f32_16x16x32_bf16 v[120:123], v[152:155], v[192:195], v[120:123]
	v_mfma_f32_16x16x32_bf16 v[116:119], v[176:179], v[192:195], v[116:119]
	v_mfma_f32_16x16x32_bf16 v[104:107], v[152:155], v[200:203], v[104:107]
	v_mfma_f32_16x16x32_bf16 v[100:103], v[176:179], v[200:203], v[100:103]
	s_setprio 3
	s_barrier
	v_mfma_f32_16x16x32_bf16 v[88:91], v[152:155], v[208:211], v[88:91]
	v_mfma_f32_16x16x32_bf16 v[84:87], v[176:179], v[208:211], v[84:87]
	s_setprio 2
	s_add_i32 s72, 0, 0x14000
	s_add_i32 s69, s69, s39
	ds_read_b128 v[212:215], v228 offset:16384
	ds_read_b128 v[216:219], v228 offset:17408
	ds_read_b128 v[220:223], v228 offset:18432
	ds_read_b128 v[224:227], v228 offset:19456
	s_mov_b32 m0, s69
	s_nop 0
	global_load_lds_dwordx4 v132, s[56:57]
	s_add_i32 m0, s69, 0x2000
	s_nop 0
	global_load_lds_dwordx4 v138, s[56:57]
	s_waitcnt lgkmcnt(0)
	s_barrier
	s_setprio 0
	v_mfma_f32_16x16x32_bf16 v[112:115], v[212:215], v[180:183], v[112:115]
	v_mfma_f32_16x16x32_bf16 v[108:111], v[220:223], v[180:183], v[108:111]
	v_mfma_f32_16x16x32_bf16 v[96:99], v[212:215], v[188:191], v[96:99]
	v_mfma_f32_16x16x32_bf16 v[92:95], v[220:223], v[188:191], v[92:95]
	v_mfma_f32_16x16x32_bf16 v[80:83], v[212:215], v[196:199], v[80:83]
	v_mfma_f32_16x16x32_bf16 v[76:79], v[220:223], v[196:199], v[76:79]
	v_mfma_f32_16x16x32_bf16 v[72:75], v[212:215], v[204:207], v[72:75]
	v_mfma_f32_16x16x32_bf16 v[68:71], v[220:223], v[204:207], v[68:71]
	v_mfma_f32_16x16x32_bf16 v[112:115], v[216:219], v[184:187], v[112:115]
	v_mfma_f32_16x16x32_bf16 v[108:111], v[224:227], v[184:187], v[108:111]
	v_mfma_f32_16x16x32_bf16 v[96:99], v[216:219], v[192:195], v[96:99]
	v_mfma_f32_16x16x32_bf16 v[92:95], v[224:227], v[192:195], v[92:95]
	v_mfma_f32_16x16x32_bf16 v[80:83], v[216:219], v[200:203], v[80:83]
	v_mfma_f32_16x16x32_bf16 v[76:79], v[224:227], v[200:203], v[76:79]
	v_mfma_f32_16x16x32_bf16 v[72:75], v[216:219], v[208:211], v[72:75]
	v_mfma_f32_16x16x32_bf16 v[68:71], v[224:227], v[208:211], v[68:71]
	s_setprio 2
	s_mov_b32 m0, s52
	s_barrier
	ds_read_b128 v[180:183], v146 offset:16384
	ds_read_b128 v[184:187], v146 offset:17408
	ds_read_b128 v[188:191], v146 offset:18432
	ds_read_b128 v[192:195], v146 offset:19456
	ds_read_b128 v[196:199], v146 offset:20480
	ds_read_b128 v[200:203], v146 offset:21504
	ds_read_b128 v[204:207], v146 offset:22528
	ds_read_b128 v[208:211], v146 offset:23552
	global_load_lds_dwordx4 v132, s[4:5]
	s_mov_b32 m0, s53
	s_nop 0
	global_load_lds_dwordx4 v138, s[4:5]
	s_waitcnt vmcnt(10)
	s_waitcnt lgkmcnt(0)
	s_barrier
	s_setprio 0
	v_mfma_f32_16x16x32_bf16 v[64:67], v[148:151], v[180:183], v[64:67]
	v_mfma_f32_16x16x32_bf16 v[60:63], v[156:159], v[180:183], v[60:63]
	v_mfma_f32_16x16x32_bf16 v[56:59], v[148:151], v[188:191], v[56:59]
	v_mfma_f32_16x16x32_bf16 v[52:55], v[156:159], v[188:191], v[52:55]
	v_mfma_f32_16x16x32_bf16 v[40:43], v[148:151], v[196:199], v[40:43]
	v_mfma_f32_16x16x32_bf16 v[36:39], v[156:159], v[196:199], v[36:39]
	v_mfma_f32_16x16x32_bf16 v[24:27], v[148:151], v[204:207], v[24:27]
	v_mfma_f32_16x16x32_bf16 v[20:23], v[156:159], v[204:207], v[20:23]
	v_mfma_f32_16x16x32_bf16 v[64:67], v[152:155], v[184:187], v[64:67]
	v_mfma_f32_16x16x32_bf16 v[60:63], v[176:179], v[184:187], v[60:63]
	v_mfma_f32_16x16x32_bf16 v[56:59], v[152:155], v[192:195], v[56:59]
	v_mfma_f32_16x16x32_bf16 v[52:55], v[176:179], v[192:195], v[52:55]
	v_mfma_f32_16x16x32_bf16 v[40:43], v[152:155], v[200:203], v[40:43]
	v_mfma_f32_16x16x32_bf16 v[36:39], v[176:179], v[200:203], v[36:39]
	s_setprio 3
	s_barrier
	v_mfma_f32_16x16x32_bf16 v[24:27], v[152:155], v[208:211], v[24:27]
	v_mfma_f32_16x16x32_bf16 v[20:23], v[176:179], v[208:211], v[20:23]
	s_setprio 2
	ds_read_b128 v[148:151], v228 offset:32768
	ds_read_b128 v[152:155], v228 offset:33792
	ds_read_b128 v[156:159], v228 offset:34816
	ds_read_b128 v[176:179], v228 offset:35840
	s_add_u32 s70, s56, 0x4000
	s_addc_u32 s71, s57, 0
	s_add_i32 s69, s72, s39
	s_mov_b32 m0, s69
	s_nop 0
	global_load_lds_dwordx4 v132, s[70:71]
	s_add_i32 m0, s69, 0x2000
	s_nop 0
	global_load_lds_dwordx4 v138, s[70:71]
	s_waitcnt vmcnt(6)
	s_barrier
; #define PG8_STAGE(bufoff, gbase, voff) do { _Pragma("unroll") for (int _i = 0; _i < 2; ++_i) \
;         __builtin_amdgcn_global_load_lds((const unsigned*)((const char*)(gbase) + (voff)[_i]), (LAS unsigned*)(lds + (bufoff) + ldsw + _i * 8192), 16, 0, 0); } while (0)
; #define PG8_LDA(dst, b, h) do { _Pragma("unroll") for (int m = 0; m < 4; ++m) _Pragma("unroll") for (int k = 0; k < 2; ++k) dst[m][k] = *(const LAS bf16x8*)(lds + PG8_SA(b, h) + aoff + m * 2048 + k * 1024); } while (0)
; #define PG8_LDB(dst, b, h) do { _Pragma("unroll") for (int n = 0; n < 2; ++n) _Pragma("unroll") for (int k = 0; k < 2; ++k) dst[n][k] = *(const LAS bf16x8*)(lds + PG8_SB(b, h) + boff + n * 2048 + k * 1024); } while (0)
; #define PG8_MMA(ai, bj, At, Bt) do { __builtin_amdgcn_s_setprio(1); _Pragma("unroll") for (int m = 0; m < 4; ++m) _Pragma("unroll") for (int n = 0; n < 2; ++n) _Pragma("unroll") for (int k = 0; k < 2; ++k) \
;         acc[ai][bj][m][n] = __builtin_amdgcn_mfma_f32_16x16x32_bf16(Bt[n][k], At[m][k], acc[ai][bj][m][n], 0, 0, 0); __builtin_amdgcn_s_setprio(0); } while (0)
; #define PG8_WAIT_V(n) asm volatile("s_waitcnt vmcnt(" #n ")" ::: "memory")
; #define PG8_WAIT_L(n) asm volatile("s_waitcnt lgkmcnt(" #n ")" ::: "memory")
; #define PG8_BAR __builtin_amdgcn_s_barrier()
; #define PG8_SCHED __builtin_amdgcn_sched_barrier(0)
; template <class Epi, class Sched, int LD>
; __device__ __forceinline__ void gemm_phase(LAS unsigned char* lds, const Gemm g, const Sched& S, const Epi& E) {
;     ...
;             PG8_WAIT_V(6); PG8_BAR; PG8_MMA(1, 1, At, B1); PG8_BAR;
;             PG8_LDB(B0, 1, 0); PG8_SCHED; PG8_LDA(At, 1, 0); PG8_STAGE(PG8_SA(0, 1), a2 + hstep, voffA);
;             PG8_WAIT_L(8); PG8_BAR; PG8_WAIT_L(0); PG8_MMA(0, 0, At, B0); PG8_BAR; PG8_SCHED;
;             PG8_LDB(B1, 1, 1); PG8_STAGE(PG8_SB(1, 0), b3, voffB);
;             PG8_BAR; PG8_WAIT_L(0); PG8_MMA(0, 1, At, B1); PG8_BAR;
;             PG8_LDA(At, 1, 1); PG8_STAGE(PG8_SA(1, 0), a3, voffA);
;             PG8_BAR; PG8_WAIT_L(0); PG8_MMA(1, 0, At, B0); PG8_BAR; PG8_SCHED;
	s_setprio 0
	v_mfma_f32_16x16x32_bf16 v[48:51], v[212:215], v[180:183], v[48:51]
	v_mfma_f32_16x16x32_bf16 v[44:47], v[220:223], v[180:183], v[44:47]
	v_mfma_f32_16x16x32_bf16 v[32:35], v[212:215], v[188:191], v[32:35]
	v_mfma_f32_16x16x32_bf16 v[28:31], v[220:223], v[188:191], v[28:31]
	v_mfma_f32_16x16x32_bf16 v[16:19], v[212:215], v[196:199], v[16:19]
	v_mfma_f32_16x16x32_bf16 v[12:15], v[220:223], v[196:199], v[12:15]
	v_mfma_f32_16x16x32_bf16 v[8:11], v[212:215], v[204:207], v[8:11]
	v_mfma_f32_16x16x32_bf16 v[4:7], v[220:223], v[204:207], v[4:7]
	v_mfma_f32_16x16x32_bf16 v[48:51], v[216:219], v[184:187], v[48:51]
	v_mfma_f32_16x16x32_bf16 v[44:47], v[224:227], v[184:187], v[44:47]
	v_mfma_f32_16x16x32_bf16 v[32:35], v[216:219], v[192:195], v[32:35]
	v_mfma_f32_16x16x32_bf16 v[28:31], v[224:227], v[192:195], v[28:31]
	v_mfma_f32_16x16x32_bf16 v[16:19], v[216:219], v[200:203], v[16:19]
	v_mfma_f32_16x16x32_bf16 v[12:15], v[224:227], v[200:203], v[12:15]
	v_mfma_f32_16x16x32_bf16 v[8:11], v[216:219], v[208:211], v[8:11]
	v_mfma_f32_16x16x32_bf16 v[4:7], v[224:227], v[208:211], v[4:7]
	s_setprio 2
	s_add_i32 s69, 0, 0x18000
	s_barrier
	s_add_u32 s4, s4, 0x4000
	s_addc_u32 s5, s5, 0
	s_mov_b32 m0, s60
	ds_read_b128 v[180:183], v146 offset:32768
	ds_read_b128 v[184:187], v146 offset:33792
	ds_read_b128 v[188:191], v146 offset:34816
	ds_read_b128 v[192:195], v146 offset:35840
	ds_read_b128 v[196:199], v146 offset:36864
	ds_read_b128 v[200:203], v146 offset:37888
	ds_read_b128 v[204:207], v146 offset:38912
	ds_read_b128 v[208:211], v146 offset:39936
	global_load_lds_dwordx4 v132, s[4:5]
	s_mov_b32 m0, s61
	s_nop 0
	global_load_lds_dwordx4 v138, s[4:5]
	s_waitcnt lgkmcnt(8)
	s_waitcnt lgkmcnt(0)
	s_barrier
	s_setprio 0
	v_mfma_f32_16x16x32_bf16 v[128:131], v[148:151], v[180:183], v[128:131]
	v_mfma_f32_16x16x32_bf16 v[124:127], v[156:159], v[180:183], v[124:127]
	v_mfma_f32_16x16x32_bf16 v[120:123], v[148:151], v[188:191], v[120:123]
	v_mfma_f32_16x16x32_bf16 v[116:119], v[156:159], v[188:191], v[116:119]
	v_mfma_f32_16x16x32_bf16 v[104:107], v[148:151], v[196:199], v[104:107]
	v_mfma_f32_16x16x32_bf16 v[100:103], v[156:159], v[196:199], v[100:103]
	v_mfma_f32_16x16x32_bf16 v[88:91], v[148:151], v[204:207], v[88:91]
	v_mfma_f32_16x16x32_bf16 v[84:87], v[156:159], v[204:207], v[84:87]
	v_mfma_f32_16x16x32_bf16 v[128:131], v[152:155], v[184:187], v[128:131]
	v_mfma_f32_16x16x32_bf16 v[124:127], v[176:179], v[184:187], v[124:127]
	v_mfma_f32_16x16x32_bf16 v[120:123], v[152:155], v[192:195], v[120:123]
	v_mfma_f32_16x16x32_bf16 v[116:119], v[176:179], v[192:195], v[116:119]
	v_mfma_f32_16x16x32_bf16 v[104:107], v[152:155], v[200:203], v[104:107]
	v_mfma_f32_16x16x32_bf16 v[100:103], v[176:179], v[200:203], v[100:103]
	s_setprio 3
	s_barrier
	v_mfma_f32_16x16x32_bf16 v[88:91], v[152:155], v[208:211], v[88:91]
	v_mfma_f32_16x16x32_bf16 v[84:87], v[176:179], v[208:211], v[84:87]
	s_setprio 2
	s_add_i32 s70, 0, 0x1c000
	s_add_u32 s4, s56, 0x8000
	s_addc_u32 s5, s57, 0
	s_add_i32 s69, s69, s39
	ds_read_b128 v[212:215], v228 offset:49152
	ds_read_b128 v[216:219], v228 offset:50176
	ds_read_b128 v[220:223], v228 offset:51200
	ds_read_b128 v[224:227], v228 offset:52224
	s_mov_b32 m0, s69
	s_nop 0
	global_load_lds_dwordx4 v132, s[4:5]
	s_add_i32 m0, s69, 0x2000
	s_nop 0
	global_load_lds_dwordx4 v138, s[4:5]
	s_waitcnt lgkmcnt(0)
	s_barrier
	s_setprio 0
	v_mfma_f32_16x16x32_bf16 v[112:115], v[212:215], v[180:183], v[112:115]
	v_mfma_f32_16x16x32_bf16 v[108:111], v[220:223], v[180:183], v[108:111]
	v_mfma_f32_16x16x32_bf16 v[96:99], v[212:215], v[188:191], v[96:99]
	v_mfma_f32_16x16x32_bf16 v[92:95], v[220:223], v[188:191], v[92:95]
	v_mfma_f32_16x16x32_bf16 v[80:83], v[212:215], v[196:199], v[80:83]
	v_mfma_f32_16x16x32_bf16 v[76:79], v[220:223], v[196:199], v[76:79]
	v_mfma_f32_16x16x32_bf16 v[72:75], v[212:215], v[204:207], v[72:75]
	v_mfma_f32_16x16x32_bf16 v[68:71], v[220:223], v[204:207], v[68:71]
	v_mfma_f32_16x16x32_bf16 v[112:115], v[216:219], v[184:187], v[112:115]
	v_mfma_f32_16x16x32_bf16 v[108:111], v[224:227], v[184:187], v[108:111]
	v_mfma_f32_16x16x32_bf16 v[96:99], v[216:219], v[192:195], v[96:99]
	v_mfma_f32_16x16x32_bf16 v[92:95], v[224:227], v[192:195], v[92:95]
	v_mfma_f32_16x16x32_bf16 v[80:83], v[216:219], v[200:203], v[80:83]
	v_mfma_f32_16x16x32_bf16 v[76:79], v[224:227], v[200:203], v[76:79]
	v_mfma_f32_16x16x32_bf16 v[72:75], v[216:219], v[208:211], v[72:75]
	v_mfma_f32_16x16x32_bf16 v[68:71], v[224:227], v[208:211], v[68:71]
	s_setprio 2
	s_mov_b32 m0, s64
	s_barrier
	ds_read_b128 v[180:183], v146 offset:49152
	ds_read_b128 v[184:187], v146 offset:50176
	ds_read_b128 v[188:191], v146 offset:51200
	ds_read_b128 v[192:195], v146 offset:52224
	ds_read_b128 v[196:199], v146 offset:53248
	ds_read_b128 v[200:203], v146 offset:54272
	ds_read_b128 v[204:207], v146 offset:55296
	ds_read_b128 v[208:211], v146 offset:56320
	global_load_lds_dwordx4 v132, s[58:59]
	s_mov_b32 m0, s65
	s_nop 0
	global_load_lds_dwordx4 v138, s[58:59]
	s_waitcnt vmcnt(10)
	s_waitcnt lgkmcnt(0)
	s_barrier
; #define PG8_STAGE(bufoff, gbase, voff) do { _Pragma("unroll") for (int _i = 0; _i < 2; ++_i) \
;         __builtin_amdgcn_global_load_lds((const unsigned*)((const char*)(gbase) + (voff)[_i]), (LAS unsigned*)(lds + (bufoff) + ldsw + _i * 8192), 16, 0, 0); } while (0)
; #define PG8_MMA(ai, bj, At, Bt) do { __builtin_amdgcn_s_setprio(1); _Pragma("unroll") for (int m = 0; m < 4; ++m) _Pragma("unroll") for (int n = 0; n < 2; ++n) _Pragma("unroll") for (int k = 0; k < 2; ++k) \
;         acc[ai][bj][m][n] = __builtin_amdgcn_mfma_f32_16x16x32_bf16(Bt[n][k], At[m][k], acc[ai][bj][m][n], 0, 0, 0); __builtin_amdgcn_s_setprio(0); } while (0)
; #define PG8_WAIT_V(n) asm volatile("s_waitcnt vmcnt(" #n ")" ::: "memory")
; #define PG8_WAIT_L(n) asm volatile("s_waitcnt lgkmcnt(" #n ")" ::: "memory")
; #define PG8_BAR __builtin_amdgcn_s_barrier()
; #define PG8_SCHED __builtin_amdgcn_sched_barrier(0)
;     __device__ __forceinline__ void operator()(const f32x4 (&acc)[2][2][4][2], const Unit& u, int wr, int wc, int fr, int fq) const {
;     ...
;         } else if (wc == 0) {
; #pragma unroll
;             for (int ai = 0; ai < 2; ++ai)
; #pragma unroll
;                 for (int m = 0; m < 4; ++m) {
;                     float* rowp = DT + (size_t)(row0 + ai * HALF + m * 16) * 32 + 8 * fq;
;                     *(f32x4*)rowp = acc[ai][0][m][0]; *(f32x4*)(rowp + 4) = acc[ai][0][m][1];
;                 }
;         }
; template <class Epi, class Sched, int LD>
; __device__ __forceinline__ void gemm_phase(LAS unsigned char* lds, const Gemm g, const Sched& S, const Epi& E) {
;     ...
;             PG8_BAR; PG8_WAIT_L(0); PG8_MMA(1, 0, At, B0); PG8_BAR; PG8_SCHED;
;             PG8_STAGE(PG8_SB(1, 1), b3 + hstep, voffB);
;             PG8_WAIT_V(6); PG8_BAR; PG8_MMA(1, 1, At, B1); PG8_BAR;
	s_setprio 0
	v_mfma_f32_16x16x32_bf16 v[64:67], v[148:151], v[180:183], v[64:67]
	v_mfma_f32_16x16x32_bf16 v[60:63], v[156:159], v[180:183], v[60:63]
	v_mfma_f32_16x16x32_bf16 v[56:59], v[148:151], v[188:191], v[56:59]
	v_mfma_f32_16x16x32_bf16 v[52:55], v[156:159], v[188:191], v[52:55]
	v_mfma_f32_16x16x32_bf16 v[40:43], v[148:151], v[196:199], v[40:43]
	v_mfma_f32_16x16x32_bf16 v[36:39], v[156:159], v[196:199], v[36:39]
	v_mfma_f32_16x16x32_bf16 v[24:27], v[148:151], v[204:207], v[24:27]
	v_mfma_f32_16x16x32_bf16 v[20:23], v[156:159], v[204:207], v[20:23]
	v_mfma_f32_16x16x32_bf16 v[64:67], v[152:155], v[184:187], v[64:67]
	v_mfma_f32_16x16x32_bf16 v[60:63], v[176:179], v[184:187], v[60:63]
	v_mfma_f32_16x16x32_bf16 v[56:59], v[152:155], v[192:195], v[56:59]
	v_mfma_f32_16x16x32_bf16 v[52:55], v[176:179], v[192:195], v[52:55]
	v_mfma_f32_16x16x32_bf16 v[40:43], v[152:155], v[200:203], v[40:43]
	v_mfma_f32_16x16x32_bf16 v[36:39], v[176:179], v[200:203], v[36:39]
	s_setprio 3
	s_barrier
	v_mfma_f32_16x16x32_bf16 v[24:27], v[152:155], v[208:211], v[24:27]
	v_mfma_f32_16x16x32_bf16 v[20:23], v[176:179], v[208:211], v[20:23]
	s_setprio 2
	ds_read_b128 v[148:151], v228
	ds_read_b128 v[152:155], v228 offset:1024
	ds_read_b128 v[156:159], v228 offset:2048
	ds_read_b128 v[176:179], v228 offset:3072
	s_add_u32 s4, s56, 0xc000
	s_addc_u32 s5, s57, 0
	s_add_i32 s56, s70, s39
	s_mov_b32 m0, s56
	s_nop 0
	global_load_lds_dwordx4 v132, s[4:5]
	s_add_i32 m0, s56, 0x2000
	s_nop 0
	global_load_lds_dwordx4 v138, s[4:5]
	s_waitcnt vmcnt(6)
	s_barrier
	s_setprio 0
	v_mfma_f32_16x16x32_bf16 v[48:51], v[212:215], v[180:183], v[48:51]
	v_mfma_f32_16x16x32_bf16 v[44:47], v[220:223], v[180:183], v[44:47]
	v_mfma_f32_16x16x32_bf16 v[32:35], v[212:215], v[188:191], v[32:35]
	v_mfma_f32_16x16x32_bf16 v[28:31], v[220:223], v[188:191], v[28:31]
	v_mfma_f32_16x16x32_bf16 v[16:19], v[212:215], v[196:199], v[16:19]
	v_mfma_f32_16x16x32_bf16 v[12:15], v[220:223], v[196:199], v[12:15]
	v_mfma_f32_16x16x32_bf16 v[8:11], v[212:215], v[204:207], v[8:11]
	v_mfma_f32_16x16x32_bf16 v[4:7], v[220:223], v[204:207], v[4:7]
	v_mfma_f32_16x16x32_bf16 v[48:51], v[216:219], v[184:187], v[48:51]
	v_mfma_f32_16x16x32_bf16 v[44:47], v[224:227], v[184:187], v[44:47]
	v_mfma_f32_16x16x32_bf16 v[32:35], v[216:219], v[192:195], v[32:35]
	v_mfma_f32_16x16x32_bf16 v[28:31], v[224:227], v[192:195], v[28:31]
	v_mfma_f32_16x16x32_bf16 v[16:19], v[216:219], v[200:203], v[16:19]
	v_mfma_f32_16x16x32_bf16 v[12:15], v[224:227], v[200:203], v[12:15]
	v_mfma_f32_16x16x32_bf16 v[8:11], v[216:219], v[208:211], v[8:11]
	v_mfma_f32_16x16x32_bf16 v[4:7], v[224:227], v[208:211], v[4:7]
	s_setprio 2
	s_add_i32 s49, s49, 2
	s_add_u32 s54, s54, 0x10000
	s_addc_u32 s55, s55, 0
	s_add_u32 s29, s29, 0x10000
	s_addc_u32 s47, s47, 0
	s_cmp_gt_u32 s49, 29
	s_barrier
	s_cbranch_scc0 .LBB0_501
	s_setprio 0
	v_lshl_add_u32 v142, s68, 8, v137
	s_cmp_gt_i32 s67, 35
	s_mov_b64 s[4:5], -1
	s_cbranch_scc0 .LBB0_506
	s_andn2_b64 vcc, exec, s[42:43]
	s_cbranch_vccnz .LBB0_505
	v_or_b32_e32 v150, 16, v142
	v_ashrrev_i32_e32 v143, 31, v142
	v_ashrrev_i32_e32 v151, 31, v150
	v_lshlrev_b64 v[148:149], 7, v[142:143]
	v_lshlrev_b64 v[150:151], 7, v[150:151]
	v_lshl_add_u64 v[148:149], v[140:141], 0, v[148:149]
	v_lshl_add_u64 v[150:151], v[140:141], 0, v[150:151]
	global_store_dwordx4 v[148:149], v[128:131], off
	global_store_dwordx4 v[148:149], v[124:127], off offset:16
	global_store_dwordx4 v[150:151], v[120:123], off
	global_store_dwordx4 v[150:151], v[116:119], off offset:16
	v_or_b32_e32 v150, 32, v142
	v_ashrrev_i32_e32 v151, 31, v150
	v_lshlrev_b64 v[150:151], 7, v[150:151]
	v_lshl_add_u64 v[150:151], v[140:141], 0, v[150:151]
	global_store_dwordx4 v[150:151], v[104:107], off
	global_store_dwordx4 v[150:151], v[100:103], off offset:16
	v_or_b32_e32 v150, 48, v142
	v_ashrrev_i32_e32 v151, 31, v150
	v_lshlrev_b64 v[150:151], 7, v[150:151]
	v_lshl_add_u64 v[150:151], v[140:141], 0, v[150:151]
	s_mov_b64 s[4:5], 0x4000
	global_store_dwordx4 v[150:151], v[88:91], off
	global_store_dwordx4 v[150:151], v[84:87], off offset:16
	v_lshl_add_u64 v[150:151], v[148:149], 0, s[4:5]
	s_movk_i32 s4, 0x4000
	v_add_co_u32_e32 v152, vcc, s4, v148
	s_mov_b64 s[4:5], 0x4800
	s_nop 0
	v_addc_co_u32_e32 v153, vcc, 0, v149, vcc
	global_store_dwordx4 v[152:153], v[64:67], off
	global_store_dwordx4 v[150:151], v[60:63], off offset:16
	v_lshl_add_u64 v[150:151], v[148:149], 0, s[4:5]
	global_store_dwordx4 v[152:153], v[56:59], off offset:2048
	global_store_dwordx4 v[150:151], v[52:55], off offset:16
	s_mov_b64 s[4:5], 0x5000
	v_add_co_u32_e32 v152, vcc, 0x5000, v148
	v_lshl_add_u64 v[150:151], v[148:149], 0, s[4:5]
	s_nop 0
	v_addc_co_u32_e32 v153, vcc, 0, v149, vcc
	s_mov_b64 s[4:5], 0x5800
	global_store_dwordx4 v[152:153], v[40:43], off
	global_store_dwordx4 v[150:151], v[36:39], off offset:16
	v_lshl_add_u64 v[148:149], v[148:149], 0, s[4:5]
	global_store_dwordx4 v[152:153], v[24:27], off offset:2048
	global_store_dwordx4 v[148:149], v[20:23], off offset:16

; #define PG8_STAGE(bufoff, gbase, voff) do { _Pragma("unroll") for (int _i = 0; _i < 2; ++_i) \
;         __builtin_amdgcn_global_load_lds((const unsigned*)((const char*)(gbase) + (voff)[_i]), (LAS unsigned*)(lds + (bufoff) + ldsw + _i * 8192), 16, 0, 0); } while (0)
; #define PG8_LDA(dst, b, h) do { _Pragma("unroll") for (int m = 0; m < 4; ++m) _Pragma("unroll") for (int k = 0; k < 2; ++k) dst[m][k] = *(const LAS bf16x8*)(lds + PG8_SA(b, h) + aoff + m * 2048 + k * 1024); } while (0)
; #define PG8_LDB(dst, b, h) do { _Pragma("unroll") for (int n = 0; n < 2; ++n) _Pragma("unroll") for (int k = 0; k < 2; ++k) dst[n][k] = *(const LAS bf16x8*)(lds + PG8_SB(b, h) + boff + n * 2048 + k * 1024); } while (0)
; #define PG8_MMA(ai, bj, At, Bt) do { __builtin_amdgcn_s_setprio(1); _Pragma("unroll") for (int m = 0; m < 4; ++m) _Pragma("unroll") for (int n = 0; n < 2; ++n) _Pragma("unroll") for (int k = 0; k < 2; ++k) \
;         acc[ai][bj][m][n] = __builtin_amdgcn_mfma_f32_16x16x32_bf16(Bt[n][k], At[m][k], acc[ai][bj][m][n], 0, 0, 0); __builtin_amdgcn_s_setprio(0); } while (0)
; #define PG8_WAIT_V(n) asm volatile("s_waitcnt vmcnt(" #n ")" ::: "memory")
; #define PG8_WAIT_L(n) asm volatile("s_waitcnt lgkmcnt(" #n ")" ::: "memory")
; template <class Epi, class Sched, int LD>
; __device__ __forceinline__ void gemm_phase(LAS unsigned char* lds, const Gemm g, const Sched& S, const Epi& E) {
;     ...
;         for (int t = 0; t < nt; t += 2) {
;             const bool last = (t == nt - 2);
;             const char* a1 = cA + (size_t)(t + 1) * kstep;
;             const char* a2 = last ? nA : cA + (size_t)(t + 2) * kstep; const char* b2 = last ? nB : cB + (size_t)(t + 2) * kstep;
;             const char* a3 = a2 + kstep; const char* b3 = b2 + kstep;
;             PG8_LDB(B0, 0, 0); PG8_SCHED; PG8_LDA(At, 0, 0); PG8_STAGE(PG8_SA(1, 1), a1 + hstep, voffA);
;             PG8_WAIT_L(8); PG8_BAR; PG8_WAIT_L(0); PG8_MMA(0, 0, At, B0); PG8_BAR; PG8_SCHED;
;             PG8_LDB(B1, 0, 1); PG8_STAGE(PG8_SB(0, 0), b2, voffB);
;             PG8_BAR; PG8_WAIT_L(0); PG8_MMA(0, 1, At, B1); PG8_BAR;
;             PG8_LDA(At, 0, 1); PG8_STAGE(PG8_SA(0, 0), a2, voffA);
;             PG8_BAR; PG8_WAIT_L(0); PG8_MMA(1, 0, At, B0); PG8_BAR; PG8_SCHED;
;             PG8_STAGE(PG8_SB(0, 1), b2 + hstep, voffB);
;             PG8_WAIT_V(6); PG8_BAR; PG8_MMA(1, 1, At, B1); PG8_BAR;
.LBB0_899:
	s_add_u32 s4, s50, 0x4000
	s_addc_u32 s5, s51, 0
	s_cmp_eq_u32 s70, 28
	s_cselect_b32 s4, s48, s4
	s_cselect_b32 s5, s49, s5
	s_cselect_b32 s54, s40, s45
	s_cselect_b32 s55, s41, s47
	s_add_u32 s56, s4, 0x8000
	s_addc_u32 s57, s5, 0
	s_add_i32 s71, 0, 0x10000
	s_add_i32 m0, s29, 0xc000
	ds_read_b128 v[180:183], v144
	ds_read_b128 v[184:187], v144 offset:1024
	ds_read_b128 v[188:191], v144 offset:2048
	ds_read_b128 v[192:195], v144 offset:3072
	ds_read_b128 v[196:199], v144 offset:4096
	ds_read_b128 v[200:203], v144 offset:5120
	ds_read_b128 v[204:207], v144 offset:6144
	ds_read_b128 v[208:211], v144 offset:7168
	global_load_lds_dwordx4 v138, s[50:51]
	s_add_i32 m0, s29, 0xe000
	s_nop 0
	global_load_lds_dwordx4 v140, s[50:51]
	s_waitcnt lgkmcnt(8)
	s_waitcnt lgkmcnt(0)
	s_barrier
	s_setprio 0
	v_mfma_f32_16x16x32_bf16 v[128:131], v[146:149], v[180:183], v[128:131]
	v_mfma_f32_16x16x32_bf16 v[120:123], v[154:157], v[180:183], v[120:123]
	v_mfma_f32_16x16x32_bf16 v[112:115], v[146:149], v[188:191], v[112:115]
	v_mfma_f32_16x16x32_bf16 v[104:107], v[154:157], v[188:191], v[104:107]
	v_mfma_f32_16x16x32_bf16 v[96:99], v[146:149], v[196:199], v[96:99]
	v_mfma_f32_16x16x32_bf16 v[88:91], v[154:157], v[196:199], v[88:91]
	v_mfma_f32_16x16x32_bf16 v[80:83], v[146:149], v[204:207], v[80:83]
	v_mfma_f32_16x16x32_bf16 v[72:75], v[154:157], v[204:207], v[72:75]
	v_mfma_f32_16x16x32_bf16 v[128:131], v[150:153], v[184:187], v[128:131]
	v_mfma_f32_16x16x32_bf16 v[120:123], v[176:179], v[184:187], v[120:123]
	v_mfma_f32_16x16x32_bf16 v[112:115], v[150:153], v[192:195], v[112:115]
	v_mfma_f32_16x16x32_bf16 v[104:107], v[176:179], v[192:195], v[104:107]
	v_mfma_f32_16x16x32_bf16 v[96:99], v[150:153], v[200:203], v[96:99]
	v_mfma_f32_16x16x32_bf16 v[88:91], v[176:179], v[200:203], v[88:91]
	s_setprio 3
	s_barrier
	v_mfma_f32_16x16x32_bf16 v[80:83], v[150:153], v[208:211], v[80:83]
	v_mfma_f32_16x16x32_bf16 v[72:75], v[176:179], v[208:211], v[72:75]
	s_setprio 2
	s_add_i32 s74, 0, 0x14000
	s_add_i32 s71, s71, s28
	s_mov_b32 m0, s71
	ds_read_b128 v[212:215], v228 offset:16384
	ds_read_b128 v[216:219], v228 offset:17408
	ds_read_b128 v[220:223], v228 offset:18432
	ds_read_b128 v[224:227], v228 offset:19456
	global_load_lds_dwordx4 v138, s[54:55]
	s_add_i32 m0, s71, 0x2000
	s_nop 0
	global_load_lds_dwordx4 v140, s[54:55]
	s_waitcnt lgkmcnt(0)
	s_barrier
	s_setprio 0
	v_mfma_f32_16x16x32_bf16 v[124:127], v[212:215], v[180:183], v[124:127]
	v_mfma_f32_16x16x32_bf16 v[116:119], v[220:223], v[180:183], v[116:119]
	v_mfma_f32_16x16x32_bf16 v[108:111], v[212:215], v[188:191], v[108:111]
	v_mfma_f32_16x16x32_bf16 v[100:103], v[220:223], v[188:191], v[100:103]
	v_mfma_f32_16x16x32_bf16 v[92:95], v[212:215], v[196:199], v[92:95]
	v_mfma_f32_16x16x32_bf16 v[84:87], v[220:223], v[196:199], v[84:87]
	v_mfma_f32_16x16x32_bf16 v[76:79], v[212:215], v[204:207], v[76:79]
	v_mfma_f32_16x16x32_bf16 v[68:71], v[220:223], v[204:207], v[68:71]
	v_mfma_f32_16x16x32_bf16 v[124:127], v[216:219], v[184:187], v[124:127]
	v_mfma_f32_16x16x32_bf16 v[116:119], v[224:227], v[184:187], v[116:119]
	v_mfma_f32_16x16x32_bf16 v[108:111], v[216:219], v[192:195], v[108:111]
	v_mfma_f32_16x16x32_bf16 v[100:103], v[224:227], v[192:195], v[100:103]
	v_mfma_f32_16x16x32_bf16 v[92:95], v[216:219], v[200:203], v[92:95]
	v_mfma_f32_16x16x32_bf16 v[84:87], v[224:227], v[200:203], v[84:87]
	v_mfma_f32_16x16x32_bf16 v[76:79], v[216:219], v[208:211], v[76:79]
	v_mfma_f32_16x16x32_bf16 v[68:71], v[224:227], v[208:211], v[68:71]
	s_setprio 2
	s_mov_b32 m0, s29
	s_barrier
	ds_read_b128 v[180:183], v144 offset:16384
	ds_read_b128 v[184:187], v144 offset:17408
	ds_read_b128 v[188:191], v144 offset:18432
	ds_read_b128 v[192:195], v144 offset:19456
	ds_read_b128 v[196:199], v144 offset:20480
	ds_read_b128 v[200:203], v144 offset:21504
	ds_read_b128 v[204:207], v144 offset:22528
	ds_read_b128 v[208:211], v144 offset:23552
	global_load_lds_dwordx4 v138, s[4:5]
	s_mov_b32 m0, s39
	s_nop 0
	global_load_lds_dwordx4 v140, s[4:5]
	s_waitcnt vmcnt(10)
	s_waitcnt lgkmcnt(0)
	s_barrier
	s_setprio 0
	v_mfma_f32_16x16x32_bf16 v[64:67], v[146:149], v[180:183], v[64:67]
	v_mfma_f32_16x16x32_bf16 v[56:59], v[154:157], v[180:183], v[56:59]
	v_mfma_f32_16x16x32_bf16 v[48:51], v[146:149], v[188:191], v[48:51]
	v_mfma_f32_16x16x32_bf16 v[40:43], v[154:157], v[188:191], v[40:43]
	v_mfma_f32_16x16x32_bf16 v[32:35], v[146:149], v[196:199], v[32:35]
	v_mfma_f32_16x16x32_bf16 v[24:27], v[154:157], v[196:199], v[24:27]
	v_mfma_f32_16x16x32_bf16 v[16:19], v[146:149], v[204:207], v[16:19]
	v_mfma_f32_16x16x32_bf16 v[8:11], v[154:157], v[204:207], v[8:11]
	v_mfma_f32_16x16x32_bf16 v[64:67], v[150:153], v[184:187], v[64:67]
	v_mfma_f32_16x16x32_bf16 v[56:59], v[176:179], v[184:187], v[56:59]
	v_mfma_f32_16x16x32_bf16 v[48:51], v[150:153], v[192:195], v[48:51]
	v_mfma_f32_16x16x32_bf16 v[40:43], v[176:179], v[192:195], v[40:43]
	v_mfma_f32_16x16x32_bf16 v[32:35], v[150:153], v[200:203], v[32:35]
	v_mfma_f32_16x16x32_bf16 v[24:27], v[176:179], v[200:203], v[24:27]
	s_setprio 3
	s_barrier
	v_mfma_f32_16x16x32_bf16 v[16:19], v[150:153], v[208:211], v[16:19]
	v_mfma_f32_16x16x32_bf16 v[8:11], v[176:179], v[208:211], v[8:11]
	s_setprio 2
	ds_read_b128 v[146:149], v228 offset:32768
	ds_read_b128 v[150:153], v228 offset:33792
	ds_read_b128 v[154:157], v228 offset:34816
	ds_read_b128 v[176:179], v228 offset:35840
	s_add_u32 s72, s54, 0x4000
	s_addc_u32 s73, s55, 0
	s_add_i32 s71, s74, s28
	s_mov_b32 m0, s71
	s_nop 0
	global_load_lds_dwordx4 v138, s[72:73]
	s_add_i32 m0, s71, 0x2000
	s_nop 0
	global_load_lds_dwordx4 v140, s[72:73]
	s_waitcnt vmcnt(6)
	s_barrier
; #define PG8_STAGE(bufoff, gbase, voff) do { _Pragma("unroll") for (int _i = 0; _i < 2; ++_i) \
;         __builtin_amdgcn_global_load_lds((const unsigned*)((const char*)(gbase) + (voff)[_i]), (LAS unsigned*)(lds + (bufoff) + ldsw + _i * 8192), 16, 0, 0); } while (0)
; #define PG8_LDA(dst, b, h) do { _Pragma("unroll") for (int m = 0; m < 4; ++m) _Pragma("unroll") for (int k = 0; k < 2; ++k) dst[m][k] = *(const LAS bf16x8*)(lds + PG8_SA(b, h) + aoff + m * 2048 + k * 1024); } while (0)
; #define PG8_LDB(dst, b, h) do { _Pragma("unroll") for (int n = 0; n < 2; ++n) _Pragma("unroll") for (int k = 0; k < 2; ++k) dst[n][k] = *(const LAS bf16x8*)(lds + PG8_SB(b, h) + boff + n * 2048 + k * 1024); } while (0)
; #define PG8_MMA(ai, bj, At, Bt) do { __builtin_amdgcn_s_setprio(1); _Pragma("unroll") for (int m = 0; m < 4; ++m) _Pragma("unroll") for (int n = 0; n < 2; ++n) _Pragma("unroll") for (int k = 0; k < 2; ++k) \
;         acc[ai][bj][m][n] = __builtin_amdgcn_mfma_f32_16x16x32_bf16(Bt[n][k], At[m][k], acc[ai][bj][m][n], 0, 0, 0); __builtin_amdgcn_s_setprio(0); } while (0)
; #define PG8_WAIT_V(n) asm volatile("s_waitcnt vmcnt(" #n ")" ::: "memory")
; #define PG8_WAIT_L(n) asm volatile("s_waitcnt lgkmcnt(" #n ")" ::: "memory")
; #define PG8_BAR __builtin_amdgcn_s_barrier()
; #define PG8_SCHED __builtin_amdgcn_sched_barrier(0)
; template <class Epi, class Sched, int LD>
; __device__ __forceinline__ void gemm_phase(LAS unsigned char* lds, const Gemm g, const Sched& S, const Epi& E) {
;     ...
;             PG8_WAIT_V(6); PG8_BAR; PG8_MMA(1, 1, At, B1); PG8_BAR;
;             PG8_LDB(B0, 1, 0); PG8_SCHED; PG8_LDA(At, 1, 0); PG8_STAGE(PG8_SA(0, 1), a2 + hstep, voffA);
;             PG8_WAIT_L(8); PG8_BAR; PG8_WAIT_L(0); PG8_MMA(0, 0, At, B0); PG8_BAR; PG8_SCHED;
;             PG8_LDB(B1, 1, 1); PG8_STAGE(PG8_SB(1, 0), b3, voffB);
;             PG8_BAR; PG8_WAIT_L(0); PG8_MMA(0, 1, At, B1); PG8_BAR;
;             PG8_LDA(At, 1, 1); PG8_STAGE(PG8_SA(1, 0), a3, voffA);
;             PG8_BAR; PG8_WAIT_L(0); PG8_MMA(1, 0, At, B0); PG8_BAR; PG8_SCHED;
	s_setprio 0
	v_mfma_f32_16x16x32_bf16 v[60:63], v[212:215], v[180:183], v[60:63]
	v_mfma_f32_16x16x32_bf16 v[52:55], v[220:223], v[180:183], v[52:55]
	v_mfma_f32_16x16x32_bf16 v[44:47], v[212:215], v[188:191], v[44:47]
	v_mfma_f32_16x16x32_bf16 v[36:39], v[220:223], v[188:191], v[36:39]
	v_mfma_f32_16x16x32_bf16 v[28:31], v[212:215], v[196:199], v[28:31]
	v_mfma_f32_16x16x32_bf16 v[20:23], v[220:223], v[196:199], v[20:23]
	v_mfma_f32_16x16x32_bf16 v[12:15], v[212:215], v[204:207], v[12:15]
	v_mfma_f32_16x16x32_bf16 v[4:7], v[220:223], v[204:207], v[4:7]
	v_mfma_f32_16x16x32_bf16 v[60:63], v[216:219], v[184:187], v[60:63]
	v_mfma_f32_16x16x32_bf16 v[52:55], v[224:227], v[184:187], v[52:55]
	v_mfma_f32_16x16x32_bf16 v[44:47], v[216:219], v[192:195], v[44:47]
	v_mfma_f32_16x16x32_bf16 v[36:39], v[224:227], v[192:195], v[36:39]
	v_mfma_f32_16x16x32_bf16 v[28:31], v[216:219], v[200:203], v[28:31]
	v_mfma_f32_16x16x32_bf16 v[20:23], v[224:227], v[200:203], v[20:23]
	v_mfma_f32_16x16x32_bf16 v[12:15], v[216:219], v[208:211], v[12:15]
	v_mfma_f32_16x16x32_bf16 v[4:7], v[224:227], v[208:211], v[4:7]
	s_setprio 2
	s_add_i32 s71, 0, 0x18000
	s_barrier
	s_add_u32 s4, s4, 0x4000
	s_addc_u32 s5, s5, 0
	s_mov_b32 m0, s52
	ds_read_b128 v[180:183], v144 offset:32768
	ds_read_b128 v[184:187], v144 offset:33792
	ds_read_b128 v[188:191], v144 offset:34816
	ds_read_b128 v[192:195], v144 offset:35840
	ds_read_b128 v[196:199], v144 offset:36864
	ds_read_b128 v[200:203], v144 offset:37888
	ds_read_b128 v[204:207], v144 offset:38912
	ds_read_b128 v[208:211], v144 offset:39936
	global_load_lds_dwordx4 v138, s[4:5]
	s_mov_b32 m0, s53
	s_nop 0
	global_load_lds_dwordx4 v140, s[4:5]
	s_waitcnt lgkmcnt(8)
	s_waitcnt lgkmcnt(0)
	s_barrier
	s_setprio 0
	v_mfma_f32_16x16x32_bf16 v[128:131], v[146:149], v[180:183], v[128:131]
	v_mfma_f32_16x16x32_bf16 v[120:123], v[154:157], v[180:183], v[120:123]
	v_mfma_f32_16x16x32_bf16 v[112:115], v[146:149], v[188:191], v[112:115]
	v_mfma_f32_16x16x32_bf16 v[104:107], v[154:157], v[188:191], v[104:107]
	v_mfma_f32_16x16x32_bf16 v[96:99], v[146:149], v[196:199], v[96:99]
	v_mfma_f32_16x16x32_bf16 v[88:91], v[154:157], v[196:199], v[88:91]
	v_mfma_f32_16x16x32_bf16 v[80:83], v[146:149], v[204:207], v[80:83]
	v_mfma_f32_16x16x32_bf16 v[72:75], v[154:157], v[204:207], v[72:75]
	v_mfma_f32_16x16x32_bf16 v[128:131], v[150:153], v[184:187], v[128:131]
	v_mfma_f32_16x16x32_bf16 v[120:123], v[176:179], v[184:187], v[120:123]
	v_mfma_f32_16x16x32_bf16 v[112:115], v[150:153], v[192:195], v[112:115]
	v_mfma_f32_16x16x32_bf16 v[104:107], v[176:179], v[192:195], v[104:107]
	v_mfma_f32_16x16x32_bf16 v[96:99], v[150:153], v[200:203], v[96:99]
	v_mfma_f32_16x16x32_bf16 v[88:91], v[176:179], v[200:203], v[88:91]
	s_setprio 3
	s_barrier
	v_mfma_f32_16x16x32_bf16 v[80:83], v[150:153], v[208:211], v[80:83]
	v_mfma_f32_16x16x32_bf16 v[72:75], v[176:179], v[208:211], v[72:75]
	s_setprio 2
	s_add_i32 s72, 0, 0x1c000
	s_add_u32 s4, s54, 0x8000
	s_addc_u32 s5, s55, 0
	s_add_i32 s71, s71, s28
	s_mov_b32 m0, s71
	ds_read_b128 v[212:215], v228 offset:49152
	ds_read_b128 v[216:219], v228 offset:50176
	ds_read_b128 v[220:223], v228 offset:51200
	ds_read_b128 v[224:227], v228 offset:52224
	global_load_lds_dwordx4 v138, s[4:5]
	s_add_i32 m0, s71, 0x2000
	s_nop 0
	global_load_lds_dwordx4 v140, s[4:5]
	s_waitcnt lgkmcnt(0)
	s_barrier
	s_setprio 0
	v_mfma_f32_16x16x32_bf16 v[124:127], v[212:215], v[180:183], v[124:127]
	v_mfma_f32_16x16x32_bf16 v[116:119], v[220:223], v[180:183], v[116:119]
	v_mfma_f32_16x16x32_bf16 v[108:111], v[212:215], v[188:191], v[108:111]
	v_mfma_f32_16x16x32_bf16 v[100:103], v[220:223], v[188:191], v[100:103]
	v_mfma_f32_16x16x32_bf16 v[92:95], v[212:215], v[196:199], v[92:95]
	v_mfma_f32_16x16x32_bf16 v[84:87], v[220:223], v[196:199], v[84:87]
	v_mfma_f32_16x16x32_bf16 v[76:79], v[212:215], v[204:207], v[76:79]
	v_mfma_f32_16x16x32_bf16 v[68:71], v[220:223], v[204:207], v[68:71]
	v_mfma_f32_16x16x32_bf16 v[124:127], v[216:219], v[184:187], v[124:127]
	v_mfma_f32_16x16x32_bf16 v[116:119], v[224:227], v[184:187], v[116:119]
	v_mfma_f32_16x16x32_bf16 v[108:111], v[216:219], v[192:195], v[108:111]
	v_mfma_f32_16x16x32_bf16 v[100:103], v[224:227], v[192:195], v[100:103]
	v_mfma_f32_16x16x32_bf16 v[92:95], v[216:219], v[200:203], v[92:95]
	v_mfma_f32_16x16x32_bf16 v[84:87], v[224:227], v[200:203], v[84:87]
	v_mfma_f32_16x16x32_bf16 v[76:79], v[216:219], v[208:211], v[76:79]
	v_mfma_f32_16x16x32_bf16 v[68:71], v[224:227], v[208:211], v[68:71]
	s_setprio 2
	s_mov_b32 m0, s60
	s_barrier
	ds_read_b128 v[180:183], v144 offset:49152
	ds_read_b128 v[184:187], v144 offset:50176
	ds_read_b128 v[188:191], v144 offset:51200
	ds_read_b128 v[192:195], v144 offset:52224
	ds_read_b128 v[196:199], v144 offset:53248
	ds_read_b128 v[200:203], v144 offset:54272
	ds_read_b128 v[204:207], v144 offset:55296
	ds_read_b128 v[208:211], v144 offset:56320
	global_load_lds_dwordx4 v138, s[56:57]
	s_mov_b32 m0, s61
	s_nop 0
	global_load_lds_dwordx4 v140, s[56:57]
	s_waitcnt vmcnt(10)
	s_waitcnt lgkmcnt(0)
	s_barrier
	s_setprio 0
	v_mfma_f32_16x16x32_bf16 v[64:67], v[146:149], v[180:183], v[64:67]
	v_mfma_f32_16x16x32_bf16 v[56:59], v[154:157], v[180:183], v[56:59]
	v_mfma_f32_16x16x32_bf16 v[48:51], v[146:149], v[188:191], v[48:51]
	v_mfma_f32_16x16x32_bf16 v[40:43], v[154:157], v[188:191], v[40:43]
	v_mfma_f32_16x16x32_bf16 v[32:35], v[146:149], v[196:199], v[32:35]
	v_mfma_f32_16x16x32_bf16 v[24:27], v[154:157], v[196:199], v[24:27]
	v_mfma_f32_16x16x32_bf16 v[16:19], v[146:149], v[204:207], v[16:19]
	v_mfma_f32_16x16x32_bf16 v[8:11], v[154:157], v[204:207], v[8:11]
	v_mfma_f32_16x16x32_bf16 v[64:67], v[150:153], v[184:187], v[64:67]
	v_mfma_f32_16x16x32_bf16 v[56:59], v[176:179], v[184:187], v[56:59]
	v_mfma_f32_16x16x32_bf16 v[48:51], v[150:153], v[192:195], v[48:51]
	v_mfma_f32_16x16x32_bf16 v[40:43], v[176:179], v[192:195], v[40:43]
	v_mfma_f32_16x16x32_bf16 v[32:35], v[150:153], v[200:203], v[32:35]
	v_mfma_f32_16x16x32_bf16 v[24:27], v[176:179], v[200:203], v[24:27]
	s_setprio 3
	s_barrier
; __device__ __forceinline__ unsigned cvt_pk_bf16(float lo, float hi) { f32x2 v = {lo, hi}; bf16x2v b = __builtin_convertvector(v, bf16x2v); return __builtin_bit_cast(unsigned, b); }
; __device__ __forceinline__ float silu_f(float x) { return x * __builtin_amdgcn_rcpf(1.f + __expf(-x)); }
; #define PG8_STAGE(bufoff, gbase, voff) do { _Pragma("unroll") for (int _i = 0; _i < 2; ++_i) \
;         __builtin_amdgcn_global_load_lds((const unsigned*)((const char*)(gbase) + (voff)[_i]), (LAS unsigned*)(lds + (bufoff) + ldsw + _i * 8192), 16, 0, 0); } while (0)
; #define PG8_MMA(ai, bj, At, Bt) do { __builtin_amdgcn_s_setprio(1); _Pragma("unroll") for (int m = 0; m < 4; ++m) _Pragma("unroll") for (int n = 0; n < 2; ++n) _Pragma("unroll") for (int k = 0; k < 2; ++k) \
;         acc[ai][bj][m][n] = __builtin_amdgcn_mfma_f32_16x16x32_bf16(Bt[n][k], At[m][k], acc[ai][bj][m][n], 0, 0, 0); __builtin_amdgcn_s_setprio(0); } while (0)
; #define PG8_WAIT_V(n) asm volatile("s_waitcnt vmcnt(" #n ")" ::: "memory")
; #define PG8_BAR __builtin_amdgcn_s_barrier()
;     __device__ __forceinline__ void operator()(const f32x4 (&acc)[2][2][4][2], const Unit& u, int wr, int wc, int fr, int fq) const {
;         const int row0 = u.pm * BM + wr * 64 + fr, col0 = u.pn * 128 + wc * 32 + 8 * fq;
; #pragma unroll
;         for (int ai = 0; ai < 2; ++ai)
; #pragma unroll
;             for (int m = 0; m < 4; ++m) {
;                 bf16_t* rowp = O + img_off(row0 + ai * HALF + m * 16, col0, D_FF / 64);
;                 const f32x4 g0 = acc[ai][0][m][0], g1 = acc[ai][0][m][1], u0 = acc[ai][1][m][0], u1 = acc[ai][1][m][1];
;                 u32x4 w;
;                 w.x = cvt_pk_bf16(silu_f(g0[0]) * u0[0], silu_f(g0[1]) * u0[1]); w.y = cvt_pk_bf16(silu_f(g0[2]) * u0[2], silu_f(g0[3]) * u0[3]);
;                 w.z = cvt_pk_bf16(silu_f(g1[0]) * u1[0], silu_f(g1[1]) * u1[1]); w.w = cvt_pk_bf16(silu_f(g1[2]) * u1[2], silu_f(g1[3]) * u1[3]);
;                 *(u32x4*)rowp = w;
; template <class Epi, class Sched, int LD>
; __device__ __forceinline__ void gemm_phase(LAS unsigned char* lds, const Gemm g, const Sched& S, const Epi& E) {
;     ...
;             PG8_BAR; PG8_WAIT_L(0); PG8_MMA(1, 0, At, B0); PG8_BAR; PG8_SCHED;
;             PG8_STAGE(PG8_SB(1, 1), b3 + hstep, voffB);
;             PG8_WAIT_V(6); PG8_BAR; PG8_MMA(1, 1, At, B1); PG8_BAR;
;         }
;         E(acc, cur, wr, wc, fr, fq);
	v_mfma_f32_16x16x32_bf16 v[16:19], v[150:153], v[208:211], v[16:19]
	v_mfma_f32_16x16x32_bf16 v[8:11], v[176:179], v[208:211], v[8:11]
	s_setprio 2
	ds_read_b128 v[146:149], v228
	ds_read_b128 v[150:153], v228 offset:1024
	ds_read_b128 v[154:157], v228 offset:2048
	ds_read_b128 v[176:179], v228 offset:3072
	s_add_u32 s4, s54, 0xc000
	s_addc_u32 s5, s55, 0
	s_add_i32 s54, s72, s28
	s_mov_b32 m0, s54
	s_nop 0
	global_load_lds_dwordx4 v138, s[4:5]
	s_add_i32 m0, s54, 0x2000
	s_nop 0
	global_load_lds_dwordx4 v140, s[4:5]
	s_waitcnt vmcnt(6)
	s_barrier
	s_setprio 0
	v_mfma_f32_16x16x32_bf16 v[60:63], v[212:215], v[180:183], v[60:63]
	v_mfma_f32_16x16x32_bf16 v[52:55], v[220:223], v[180:183], v[52:55]
	v_mfma_f32_16x16x32_bf16 v[44:47], v[212:215], v[188:191], v[44:47]
	v_mfma_f32_16x16x32_bf16 v[36:39], v[220:223], v[188:191], v[36:39]
	v_mfma_f32_16x16x32_bf16 v[28:31], v[212:215], v[196:199], v[28:31]
	v_mfma_f32_16x16x32_bf16 v[20:23], v[220:223], v[196:199], v[20:23]
	v_mfma_f32_16x16x32_bf16 v[12:15], v[212:215], v[204:207], v[12:15]
	v_mfma_f32_16x16x32_bf16 v[4:7], v[220:223], v[204:207], v[4:7]
	v_mfma_f32_16x16x32_bf16 v[60:63], v[216:219], v[184:187], v[60:63]
	v_mfma_f32_16x16x32_bf16 v[52:55], v[224:227], v[184:187], v[52:55]
	v_mfma_f32_16x16x32_bf16 v[44:47], v[216:219], v[192:195], v[44:47]
	v_mfma_f32_16x16x32_bf16 v[36:39], v[224:227], v[192:195], v[36:39]
	v_mfma_f32_16x16x32_bf16 v[28:31], v[216:219], v[200:203], v[28:31]
	v_mfma_f32_16x16x32_bf16 v[20:23], v[224:227], v[200:203], v[20:23]
	v_mfma_f32_16x16x32_bf16 v[12:15], v[216:219], v[208:211], v[12:15]
	v_mfma_f32_16x16x32_bf16 v[4:7], v[224:227], v[208:211], v[4:7]
	s_setprio 2
	s_add_i32 s70, s70, 2
	s_add_u32 s50, s50, 0x10000
	s_addc_u32 s51, s51, 0
	s_add_u32 s45, s45, 0x10000
	s_addc_u32 s47, s47, 0
	s_cmp_gt_u32 s70, 29
	s_barrier
	s_cbranch_scc0 .LBB0_899
	s_setprio 0
	v_mul_f32_e32 v148, 0xbfb8aa3b, v128
	v_mul_f32_e32 v149, 0xbfb8aa3b, v129
	v_exp_f32_e32 v148, v148
	v_exp_f32_e32 v149, v149
	s_lshl_b32 s5, s69, 8
	s_add_i32 s5, s5, s58
	v_add_f32_e32 v148, 1.0, v148
	v_add_f32_e32 v149, 1.0, v149
	v_rcp_f32_e32 v148, v148
	v_rcp_f32_e32 v149, v149
	s_lshl_b32 s4, s68, 7
	s_or_b32 s4, s4, s59
	s_ashr_i32 s45, s5, 8
	v_pk_mul_f32 v[128:129], v[128:129], v[148:149]
	s_ashr_i32 s4, s4, 6
	v_pk_mul_f32 v[124:125], v[128:129], v[124:125]
	s_mulk_i32 s45, 0x58
	v_cvt_pk_bf16_f32 v124, v124, v125
	v_mul_f32_e32 v125, 0xbfb8aa3b, v130
	v_exp_f32_e32 v125, v125
	s_add_i32 s50, s45, s4
	s_ashr_i32 s51, s50, 31
	s_lshl_b64 s[50:51], s[50:51], 15
	v_add_f32_e32 v125, 1.0, v125
	v_rcp_f32_e32 v128, v125
	v_mul_f32_e32 v125, 0xbfb8aa3b, v131
	v_exp_f32_e32 v125, v125
	s_add_u32 s45, s16, s50
	s_addc_u32 s47, s17, s51
	s_lshl_b32 s50, s5, 7
	v_add_f32_e32 v125, 1.0, v125
	v_rcp_f32_e32 v129, v125
	s_and_b32 s50, s50, 0x4000
	s_add_u32 s50, s45, s50
	s_addc_u32 s51, s47, 0
	v_pk_mul_f32 v[128:129], v[130:131], v[128:129]
	s_or_b32 s45, s5, 16
	v_pk_mul_f32 v[126:127], v[128:129], v[126:127]
	s_lshr_b32 s45, s45, 3
	v_cvt_pk_bf16_f32 v125, v126, v127
	v_mul_f32_e32 v126, 0xbfb8aa3b, v120
	v_mul_f32_e32 v127, 0xbfb8aa3b, v121
	v_exp_f32_e32 v126, v126
	v_exp_f32_e32 v127, v127
	v_or_b32_e32 v145, s5, v137
	s_and_b32 s45, s45, 10
	v_add_f32_e32 v126, 1.0, v126
	v_add_f32_e32 v127, 1.0, v127
	v_rcp_f32_e32 v126, v126
	v_rcp_f32_e32 v127, v127
	v_lshlrev_b32_e32 v132, 6, v145
	v_lshlrev_b32_e32 v146, 2, v145
	s_or_b32 s45, s45, s64
	v_pk_mul_f32 v[120:121], v[120:121], v[126:127]
	v_and_or_b32 v132, v132, s15, v142
	v_pk_mul_f32 v[116:117], v[120:121], v[116:117]
	v_and_b32_e32 v146, 32, v146
	v_cvt_pk_bf16_f32 v126, v116, v117
	v_mul_f32_e32 v116, 0xbfb8aa3b, v122
	v_mul_f32_e32 v117, 0xbfb8aa3b, v123
	v_exp_f32_e32 v116, v116
	v_exp_f32_e32 v117, v117
	s_lshl_b32 s45, s45, 10
	v_bitop3_b32 v147, v132, s65, v146 bitop3:0xde
	v_add_f32_e32 v116, 1.0, v116
	v_add_f32_e32 v117, 1.0, v117
	v_rcp_f32_e32 v116, v116
	v_rcp_f32_e32 v117, v117
	s_and_b64 vcc, exec, s[42:43]
	s_mov_b32 s68, s44
	s_mov_b32 s69, s46
	v_pk_mul_f32 v[116:117], v[122:123], v[116:117]
	s_mov_b64 s[54:55], s[40:41]
	v_pk_mul_f32 v[116:117], v[116:117], v[118:119]
	v_bitop3_b32 v118, v132, s45, v146 bitop3:0xde
	v_cvt_pk_bf16_f32 v127, v116, v117
	v_mul_f32_e32 v116, 0xbfb8aa3b, v112
	v_mul_f32_e32 v117, 0xbfb8aa3b, v113
	v_exp_f32_e32 v116, v116
	v_exp_f32_e32 v117, v117
	s_or_b32 s45, s5, 32
	s_or_b32 s5, s5, 48
	v_add_f32_e32 v116, 1.0, v116
	v_add_f32_e32 v117, 1.0, v117
	v_rcp_f32_e32 v116, v116
	v_rcp_f32_e32 v117, v117
	s_lshr_b32 s45, s45, 3
	s_lshr_b32 s5, s5, 3
	s_and_b32 s45, s45, 12
	v_pk_mul_f32 v[112:113], v[112:113], v[116:117]
	s_and_b32 s5, s5, 14
	v_pk_mul_f32 v[108:109], v[112:113], v[108:109]
	s_or_b32 s45, s45, s64
	v_cvt_pk_bf16_f32 v108, v108, v109
	v_mul_f32_e32 v109, 0xbfb8aa3b, v114
	v_exp_f32_e32 v109, v109
	s_or_b32 s5, s5, s64
	s_lshl_b32 s45, s45, 10
	s_lshl_b32 s5, s5, 10
	v_add_f32_e32 v109, 1.0, v109
	v_rcp_f32_e32 v112, v109
	v_mul_f32_e32 v109, 0xbfb8aa3b, v115
	v_exp_f32_e32 v109, v109
	global_store_dwordx4 v147, v[124:127], s[50:51]
	v_add_f32_e32 v109, 1.0, v109
	v_rcp_f32_e32 v113, v109
	s_nop 0
	v_pk_mul_f32 v[112:113], v[114:115], v[112:113]
	s_nop 0
	v_pk_mul_f32 v[110:111], v[112:113], v[110:111]
	s_nop 0
	v_cvt_pk_bf16_f32 v109, v110, v111
	v_mul_f32_e32 v110, 0xbfb8aa3b, v104
	v_mul_f32_e32 v111, 0xbfb8aa3b, v105
	v_exp_f32_e32 v110, v110
	v_exp_f32_e32 v111, v111
	v_add_f32_e32 v110, 1.0, v110
	v_add_f32_e32 v111, 1.0, v111
	v_rcp_f32_e32 v110, v110
	v_rcp_f32_e32 v111, v111
	s_nop 0
	v_pk_mul_f32 v[104:105], v[104:105], v[110:111]
	s_nop 0
; __device__ __forceinline__ unsigned cvt_pk_bf16(float lo, float hi) { f32x2 v = {lo, hi}; bf16x2v b = __builtin_convertvector(v, bf16x2v); return __builtin_bit_cast(unsigned, b); }
; __device__ __forceinline__ float silu_f(float x) { return x * __builtin_amdgcn_rcpf(1.f + __expf(-x)); }
;     __device__ __forceinline__ void operator()(const f32x4 (&acc)[2][2][4][2], const Unit& u, int wr, int wc, int fr, int fq) const {
;     ...
;                 bf16_t* rowp = O + img_off(row0 + ai * HALF + m * 16, col0, D_FF / 64);
;                 const f32x4 g0 = acc[ai][0][m][0], g1 = acc[ai][0][m][1], u0 = acc[ai][1][m][0], u1 = acc[ai][1][m][1];
;                 u32x4 w;
;                 w.x = cvt_pk_bf16(silu_f(g0[0]) * u0[0], silu_f(g0[1]) * u0[1]); w.y = cvt_pk_bf16(silu_f(g0[2]) * u0[2], silu_f(g0[3]) * u0[3]);
;                 w.z = cvt_pk_bf16(silu_f(g1[0]) * u1[0], silu_f(g1[1]) * u1[1]); w.w = cvt_pk_bf16(silu_f(g1[2]) * u1[2], silu_f(g1[3]) * u1[3]);
;                 *(u32x4*)rowp = w;
	v_pk_mul_f32 v[100:101], v[104:105], v[100:101]
	s_nop 0
	v_cvt_pk_bf16_f32 v110, v100, v101
	v_mul_f32_e32 v100, 0xbfb8aa3b, v106
	v_mul_f32_e32 v101, 0xbfb8aa3b, v107
	v_exp_f32_e32 v100, v100
	v_exp_f32_e32 v101, v101
	v_add_f32_e32 v100, 1.0, v100
	v_add_f32_e32 v101, 1.0, v101
	v_rcp_f32_e32 v100, v100
	v_rcp_f32_e32 v101, v101
	s_nop 0
	v_pk_mul_f32 v[100:101], v[106:107], v[100:101]
	s_nop 0
	v_pk_mul_f32 v[100:101], v[100:101], v[102:103]
	v_bitop3_b32 v102, v132, s45, v146 bitop3:0xde
	v_cvt_pk_bf16_f32 v111, v100, v101
	v_mul_f32_e32 v100, 0xbfb8aa3b, v96
	v_mul_f32_e32 v101, 0xbfb8aa3b, v97
	v_exp_f32_e32 v100, v100
	v_exp_f32_e32 v101, v101
	global_store_dwordx4 v118, v[108:111], s[50:51]
	v_add_f32_e32 v100, 1.0, v100
	v_add_f32_e32 v101, 1.0, v101
	v_rcp_f32_e32 v100, v100
	v_rcp_f32_e32 v101, v101
	s_nop 0
	v_pk_mul_f32 v[96:97], v[96:97], v[100:101]
	s_nop 0
	v_pk_mul_f32 v[92:93], v[96:97], v[92:93]
	s_nop 0
	v_cvt_pk_bf16_f32 v92, v92, v93
	v_mul_f32_e32 v93, 0xbfb8aa3b, v98
	v_exp_f32_e32 v93, v93
	s_nop 0
	v_add_f32_e32 v93, 1.0, v93
	v_rcp_f32_e32 v96, v93
	v_mul_f32_e32 v93, 0xbfb8aa3b, v99
	v_exp_f32_e32 v93, v93
	s_nop 0
	v_add_f32_e32 v93, 1.0, v93
	v_rcp_f32_e32 v97, v93
	s_nop 0
	v_pk_mul_f32 v[96:97], v[98:99], v[96:97]
	s_nop 0
	v_pk_mul_f32 v[94:95], v[96:97], v[94:95]
	s_nop 0
	v_cvt_pk_bf16_f32 v93, v94, v95
	v_mul_f32_e32 v94, 0xbfb8aa3b, v88
	v_mul_f32_e32 v95, 0xbfb8aa3b, v89
	v_exp_f32_e32 v94, v94
	v_exp_f32_e32 v95, v95
	v_add_f32_e32 v94, 1.0, v94
	v_add_f32_e32 v95, 1.0, v95
	v_rcp_f32_e32 v94, v94
	v_rcp_f32_e32 v95, v95
	s_nop 0
	v_pk_mul_f32 v[88:89], v[88:89], v[94:95]
	s_nop 0
	v_pk_mul_f32 v[84:85], v[88:89], v[84:85]
	s_nop 0
	v_cvt_pk_bf16_f32 v94, v84, v85
	v_mul_f32_e32 v84, 0xbfb8aa3b, v90
	v_mul_f32_e32 v85, 0xbfb8aa3b, v91
	v_exp_f32_e32 v84, v84
	v_exp_f32_e32 v85, v85
	v_add_f32_e32 v84, 1.0, v84
	v_add_f32_e32 v85, 1.0, v85
	v_rcp_f32_e32 v84, v84
	v_rcp_f32_e32 v85, v85
	s_nop 0
	v_pk_mul_f32 v[84:85], v[90:91], v[84:85]
	s_nop 0
	v_pk_mul_f32 v[84:85], v[84:85], v[86:87]
	v_bitop3_b32 v86, v132, s5, v146 bitop3:0xde
	v_cvt_pk_bf16_f32 v95, v84, v85
	v_mul_f32_e32 v84, 0xbfb8aa3b, v80
	v_mul_f32_e32 v85, 0xbfb8aa3b, v81
	v_exp_f32_e32 v84, v84
	v_exp_f32_e32 v85, v85
	global_store_dwordx4 v102, v[92:95], s[50:51]
	v_add_f32_e32 v84, 1.0, v84
	v_add_f32_e32 v85, 1.0, v85
	v_rcp_f32_e32 v84, v84
	v_rcp_f32_e32 v85, v85
	s_nop 0
	v_pk_mul_f32 v[80:81], v[80:81], v[84:85]
	s_nop 0
	v_pk_mul_f32 v[76:77], v[80:81], v[76:77]
	s_nop 0
	v_cvt_pk_bf16_f32 v76, v76, v77
	v_mul_f32_e32 v77, 0xbfb8aa3b, v82
	v_exp_f32_e32 v77, v77
	s_nop 0
	v_add_f32_e32 v77, 1.0, v77
	v_rcp_f32_e32 v80, v77
	v_mul_f32_e32 v77, 0xbfb8aa3b, v83
	v_exp_f32_e32 v77, v77
	s_nop 0
	v_add_f32_e32 v77, 1.0, v77
	v_rcp_f32_e32 v81, v77
	s_nop 0
	v_pk_mul_f32 v[80:81], v[82:83], v[80:81]
	s_nop 0
	v_pk_mul_f32 v[78:79], v[80:81], v[78:79]
	s_nop 0
	v_cvt_pk_bf16_f32 v77, v78, v79
	v_mul_f32_e32 v78, 0xbfb8aa3b, v72
	v_mul_f32_e32 v79, 0xbfb8aa3b, v73
	v_exp_f32_e32 v78, v78
	v_exp_f32_e32 v79, v79
	v_add_f32_e32 v78, 1.0, v78
	v_add_f32_e32 v79, 1.0, v79
	v_rcp_f32_e32 v78, v78
	v_rcp_f32_e32 v79, v79
	s_nop 0
	v_pk_mul_f32 v[72:73], v[72:73], v[78:79]
	s_nop 0
	v_pk_mul_f32 v[68:69], v[72:73], v[68:69]
	v_mul_f32_e32 v73, 0xbfb8aa3b, v65
	v_cvt_pk_bf16_f32 v78, v68, v69
	v_mul_f32_e32 v68, 0xbfb8aa3b, v74
	v_mul_f32_e32 v69, 0xbfb8aa3b, v75
	v_exp_f32_e32 v68, v68
	v_exp_f32_e32 v69, v69
	v_exp_f32_e32 v73, v73
	v_add_f32_e32 v68, 1.0, v68
	v_add_f32_e32 v69, 1.0, v69
	v_rcp_f32_e32 v68, v68
	v_rcp_f32_e32 v69, v69
	v_add_f32_e32 v73, 1.0, v73
	v_rcp_f32_e32 v73, v73
	v_pk_mul_f32 v[68:69], v[74:75], v[68:69]
	s_nop 0
	v_pk_mul_f32 v[68:69], v[68:69], v[70:71]
	v_add_u32_e32 v70, 0x80, v145
	v_lshlrev_b32_e32 v71, 6, v70
	v_lshlrev_b32_e32 v72, 2, v70
	v_and_or_b32 v71, v71, s15, v142
	v_and_b32_e32 v72, 32, v72
	v_bitop3_b32 v132, v71, s65, v72 bitop3:0xde
	v_mul_f32_e32 v72, 0xbfb8aa3b, v64
	v_exp_f32_e32 v72, v72
	v_cvt_pk_bf16_f32 v79, v68, v69
	v_lshrrev_b32_e32 v68, 8, v70
	v_mov_b32_e32 v69, s4
	v_add_f32_e32 v72, 1.0, v72
	v_rcp_f32_e32 v72, v72
	s_movk_i32 s4, 0x58
	v_mad_i32_i24 v68, v68, s4, v69
	v_ashrrev_i32_e32 v69, 31, v68
	v_pk_mul_f32 v[64:65], v[64:65], v[72:73]
	v_lshlrev_b64 v[68:69], 15, v[68:69]
	v_pk_mul_f32 v[60:61], v[64:65], v[60:61]
	v_lshlrev_b32_e32 v70, 7, v70
	v_cvt_pk_bf16_f32 v60, v60, v61
	v_mul_f32_e32 v61, 0xbfb8aa3b, v66
	v_exp_f32_e32 v61, v61
	v_lshl_add_u64 v[68:69], s[16:17], 0, v[68:69]
	v_and_b32_e32 v70, 0x4000, v70
	v_mov_b32_e32 v71, v133
	v_add_f32_e32 v61, 1.0, v61
	v_rcp_f32_e32 v64, v61
	v_mul_f32_e32 v61, 0xbfb8aa3b, v67
	v_exp_f32_e32 v61, v61
	v_lshl_add_u64 v[70:71], v[68:69], 0, v[70:71]
	v_lshl_add_u64 v[70:71], v[70:71], 0, v[132:133]
	s_mov_b64 s[4:5], s[48:49]
	v_add_f32_e32 v61, 1.0, v61
	v_rcp_f32_e32 v65, v61
	global_store_dwordx4 v86, v[76:79], s[50:51]
	v_pk_mul_f32 v[64:65], v[66:67], v[64:65]
	s_nop 0
	v_pk_mul_f32 v[62:63], v[64:65], v[62:63]
	s_nop 0
	v_cvt_pk_bf16_f32 v61, v62, v63
	v_mul_f32_e32 v62, 0xbfb8aa3b, v56
	v_mul_f32_e32 v63, 0xbfb8aa3b, v57
	v_exp_f32_e32 v62, v62
	v_exp_f32_e32 v63, v63
	v_add_f32_e32 v62, 1.0, v62
	v_add_f32_e32 v63, 1.0, v63
	v_rcp_f32_e32 v62, v62
	v_rcp_f32_e32 v63, v63
	s_nop 0
	v_pk_mul_f32 v[56:57], v[56:57], v[62:63]
	s_nop 0
	v_pk_mul_f32 v[52:53], v[56:57], v[52:53]
	s_nop 0
	v_cvt_pk_bf16_f32 v62, v52, v53
	v_mul_f32_e32 v52, 0xbfb8aa3b, v58
	v_mul_f32_e32 v53, 0xbfb8aa3b, v59
	v_exp_f32_e32 v52, v52
	v_exp_f32_e32 v53, v53
	v_add_f32_e32 v52, 1.0, v52
	v_add_f32_e32 v53, 1.0, v53
	v_rcp_f32_e32 v52, v52
; __device__ __forceinline__ unsigned cvt_pk_bf16(float lo, float hi) { f32x2 v = {lo, hi}; bf16x2v b = __builtin_convertvector(v, bf16x2v); return __builtin_bit_cast(unsigned, b); }
; __device__ __forceinline__ float silu_f(float x) { return x * __builtin_amdgcn_rcpf(1.f + __expf(-x)); }
; #define PG8_WAIT_V(n) asm volatile("s_waitcnt vmcnt(" #n ")" ::: "memory")
; #define PG8_BAR __builtin_amdgcn_s_barrier()
;     __device__ __forceinline__ void operator()(const f32x4 (&acc)[2][2][4][2], const Unit& u, int wr, int wc, int fr, int fq) const {
;     ...
;                 bf16_t* rowp = O + img_off(row0 + ai * HALF + m * 16, col0, D_FF / 64);
;                 const f32x4 g0 = acc[ai][0][m][0], g1 = acc[ai][0][m][1], u0 = acc[ai][1][m][0], u1 = acc[ai][1][m][1];
;                 u32x4 w;
;                 w.x = cvt_pk_bf16(silu_f(g0[0]) * u0[0], silu_f(g0[1]) * u0[1]); w.y = cvt_pk_bf16(silu_f(g0[2]) * u0[2], silu_f(g0[3]) * u0[3]);
;                 w.z = cvt_pk_bf16(silu_f(g1[0]) * u1[0], silu_f(g1[1]) * u1[1]); w.w = cvt_pk_bf16(silu_f(g1[2]) * u1[2], silu_f(g1[3]) * u1[3]);
;                 *(u32x4*)rowp = w;
; template <class Epi, class Sched, int LD>
; __device__ __forceinline__ void gemm_phase(LAS unsigned char* lds, const Gemm g, const Sched& S, const Epi& E) {
;     ...
;         E(acc, cur, wr, wc, fr, fq);
;         if (!has_next) break;
; #pragma unroll
;         for (int a = 0; a < 2; ++a)
; #pragma unroll
;             for (int b = 0; b < 2; ++b)
; #pragma unroll
;                 for (int m = 0; m < 4; ++m)
; #pragma unroll
;                     for (int n = 0; n < 2; ++n) acc[a][b][m][n] = (f32x4){0.f, 0.f, 0.f, 0.f};
;         cur = nxt; cA = nA; cB = nB; ++ui;
;     }
;     PG8_WAIT_V(0);
;     if (wr == 0) PG8_BAR;
	v_rcp_f32_e32 v53, v53
	s_nop 0
	v_pk_mul_f32 v[52:53], v[58:59], v[52:53]
	s_nop 0
	v_pk_mul_f32 v[52:53], v[52:53], v[54:55]
	s_nop 0
	v_cvt_pk_bf16_f32 v63, v52, v53
	v_add_u32_e32 v52, 0x90, v145
	v_lshrrev_b32_e32 v54, 3, v52
	v_lshlrev_b32_e32 v53, 6, v52
	v_and_or_b32 v54, v54, 10, s64
	v_lshlrev_b32_e32 v55, 2, v52
	v_and_or_b32 v53, v53, s15, v142
	v_lshlrev_b32_e32 v54, 10, v54
	v_and_b32_e32 v55, 32, v55
	v_bitop3_b32 v132, v53, v54, v55 bitop3:0xde
	v_mul_f32_e32 v54, 0xbfb8aa3b, v48
	v_mul_f32_e32 v55, 0xbfb8aa3b, v49
	v_exp_f32_e32 v54, v54
	v_exp_f32_e32 v55, v55
	v_lshlrev_b32_e32 v52, 7, v52
	v_and_b32_e32 v52, 0x4000, v52
	v_add_f32_e32 v54, 1.0, v54
	v_add_f32_e32 v55, 1.0, v55
	v_rcp_f32_e32 v54, v54
	v_rcp_f32_e32 v55, v55
	v_mov_b32_e32 v53, v133
	v_lshl_add_u64 v[52:53], v[68:69], 0, v[52:53]
	v_lshl_add_u64 v[52:53], v[52:53], 0, v[132:133]
	v_pk_mul_f32 v[48:49], v[48:49], v[54:55]
	global_store_dwordx4 v[70:71], v[60:63], off
	v_pk_mul_f32 v[44:45], v[48:49], v[44:45]
	s_nop 0
	v_cvt_pk_bf16_f32 v44, v44, v45
	v_mul_f32_e32 v45, 0xbfb8aa3b, v50
	v_exp_f32_e32 v45, v45
	s_nop 0
	v_add_f32_e32 v45, 1.0, v45
	v_rcp_f32_e32 v48, v45
	v_mul_f32_e32 v45, 0xbfb8aa3b, v51
	v_exp_f32_e32 v45, v45
	s_nop 0
	v_add_f32_e32 v45, 1.0, v45
	v_rcp_f32_e32 v49, v45
	s_nop 0
	v_pk_mul_f32 v[48:49], v[50:51], v[48:49]
	s_nop 0
	v_pk_mul_f32 v[46:47], v[48:49], v[46:47]
	s_nop 0
	v_cvt_pk_bf16_f32 v45, v46, v47
	v_mul_f32_e32 v46, 0xbfb8aa3b, v40
	v_mul_f32_e32 v47, 0xbfb8aa3b, v41
	v_exp_f32_e32 v46, v46
	v_exp_f32_e32 v47, v47
	v_add_f32_e32 v46, 1.0, v46
	v_add_f32_e32 v47, 1.0, v47
	v_rcp_f32_e32 v46, v46
	v_rcp_f32_e32 v47, v47
	s_nop 0
	v_pk_mul_f32 v[40:41], v[40:41], v[46:47]
	s_nop 0
	v_pk_mul_f32 v[36:37], v[40:41], v[36:37]
	s_nop 0
	v_cvt_pk_bf16_f32 v46, v36, v37
	v_mul_f32_e32 v36, 0xbfb8aa3b, v42
	v_mul_f32_e32 v37, 0xbfb8aa3b, v43
	v_exp_f32_e32 v36, v36
	v_exp_f32_e32 v37, v37
	v_add_f32_e32 v36, 1.0, v36
	v_add_f32_e32 v37, 1.0, v37
	v_rcp_f32_e32 v36, v36
	v_rcp_f32_e32 v37, v37
	s_nop 0
	v_pk_mul_f32 v[36:37], v[42:43], v[36:37]
	s_nop 0
	v_pk_mul_f32 v[36:37], v[36:37], v[38:39]
	s_nop 0
	v_cvt_pk_bf16_f32 v47, v36, v37
	v_add_u32_e32 v36, 0xa0, v145
	v_lshrrev_b32_e32 v38, 3, v36
	v_lshlrev_b32_e32 v37, 6, v36
	v_and_or_b32 v38, v38, 12, s64
	v_lshlrev_b32_e32 v39, 2, v36
	v_and_or_b32 v37, v37, s15, v142
	v_lshlrev_b32_e32 v38, 10, v38
	v_and_b32_e32 v39, 32, v39
	v_bitop3_b32 v132, v37, v38, v39 bitop3:0xde
	v_mul_f32_e32 v38, 0xbfb8aa3b, v32
	v_mul_f32_e32 v39, 0xbfb8aa3b, v33
	v_exp_f32_e32 v38, v38
	v_exp_f32_e32 v39, v39
	v_lshlrev_b32_e32 v36, 7, v36
	v_and_b32_e32 v36, 0x4000, v36
	v_add_f32_e32 v38, 1.0, v38
	v_add_f32_e32 v39, 1.0, v39
	v_rcp_f32_e32 v38, v38
	v_rcp_f32_e32 v39, v39
	v_mov_b32_e32 v37, v133
	v_lshl_add_u64 v[36:37], v[68:69], 0, v[36:37]
	v_lshl_add_u64 v[36:37], v[36:37], 0, v[132:133]
	v_pk_mul_f32 v[32:33], v[32:33], v[38:39]
	global_store_dwordx4 v[52:53], v[44:47], off
	v_pk_mul_f32 v[28:29], v[32:33], v[28:29]
	s_nop 0
	v_cvt_pk_bf16_f32 v28, v28, v29
	v_mul_f32_e32 v29, 0xbfb8aa3b, v34
	v_exp_f32_e32 v29, v29
	s_nop 0
	v_add_f32_e32 v29, 1.0, v29
	v_rcp_f32_e32 v32, v29
	v_mul_f32_e32 v29, 0xbfb8aa3b, v35
	v_exp_f32_e32 v29, v29
	s_nop 0
	v_add_f32_e32 v29, 1.0, v29
	v_rcp_f32_e32 v33, v29
	s_nop 0
	v_pk_mul_f32 v[32:33], v[34:35], v[32:33]
	s_nop 0
	v_pk_mul_f32 v[30:31], v[32:33], v[30:31]
	s_nop 0
	v_cvt_pk_bf16_f32 v29, v30, v31
	v_mul_f32_e32 v30, 0xbfb8aa3b, v24
	v_mul_f32_e32 v31, 0xbfb8aa3b, v25
	v_exp_f32_e32 v30, v30
	v_exp_f32_e32 v31, v31
	v_add_f32_e32 v30, 1.0, v30
	v_add_f32_e32 v31, 1.0, v31
	v_rcp_f32_e32 v30, v30
	v_rcp_f32_e32 v31, v31
	s_nop 0
	v_pk_mul_f32 v[24:25], v[24:25], v[30:31]
	s_nop 0
	v_pk_mul_f32 v[20:21], v[24:25], v[20:21]
	s_nop 0
	v_cvt_pk_bf16_f32 v30, v20, v21
	v_mul_f32_e32 v20, 0xbfb8aa3b, v26
	v_mul_f32_e32 v21, 0xbfb8aa3b, v27
	v_exp_f32_e32 v20, v20
	v_exp_f32_e32 v21, v21
	v_add_f32_e32 v20, 1.0, v20
	v_add_f32_e32 v21, 1.0, v21
	v_rcp_f32_e32 v20, v20
	v_rcp_f32_e32 v21, v21
	s_nop 0
	v_pk_mul_f32 v[20:21], v[26:27], v[20:21]
	s_nop 0
	v_pk_mul_f32 v[20:21], v[20:21], v[22:23]
	s_nop 0
	v_cvt_pk_bf16_f32 v31, v20, v21
	v_add_u32_e32 v20, 0xb0, v145
	v_lshrrev_b32_e32 v22, 3, v20
	v_lshlrev_b32_e32 v21, 6, v20
	v_and_or_b32 v22, v22, 14, s64
	v_lshlrev_b32_e32 v23, 2, v20
	v_and_or_b32 v21, v21, s15, v142
	v_lshlrev_b32_e32 v22, 10, v22
	v_and_b32_e32 v23, 32, v23
	v_bitop3_b32 v132, v21, v22, v23 bitop3:0xde
	v_mul_f32_e32 v22, 0xbfb8aa3b, v16
	v_mul_f32_e32 v23, 0xbfb8aa3b, v17
	v_exp_f32_e32 v22, v22
	v_exp_f32_e32 v23, v23
	v_lshlrev_b32_e32 v20, 7, v20
	v_and_b32_e32 v20, 0x4000, v20
	v_add_f32_e32 v22, 1.0, v22
	v_add_f32_e32 v23, 1.0, v23
	v_rcp_f32_e32 v22, v22
	v_rcp_f32_e32 v23, v23
	v_mov_b32_e32 v21, v133
	v_lshl_add_u64 v[20:21], v[68:69], 0, v[20:21]
	v_lshl_add_u64 v[20:21], v[20:21], 0, v[132:133]
	v_pk_mul_f32 v[16:17], v[16:17], v[22:23]
	global_store_dwordx4 v[36:37], v[28:31], off
	v_pk_mul_f32 v[12:13], v[16:17], v[12:13]
	s_nop 0
	v_cvt_pk_bf16_f32 v12, v12, v13
	v_mul_f32_e32 v13, 0xbfb8aa3b, v18
	v_exp_f32_e32 v13, v13
	s_nop 0
	v_add_f32_e32 v13, 1.0, v13
	v_rcp_f32_e32 v16, v13
	v_mul_f32_e32 v13, 0xbfb8aa3b, v19
	v_exp_f32_e32 v13, v13
	s_nop 0
	v_add_f32_e32 v13, 1.0, v13
	v_rcp_f32_e32 v17, v13
	s_nop 0
	v_pk_mul_f32 v[16:17], v[18:19], v[16:17]
	s_nop 0
	v_pk_mul_f32 v[14:15], v[16:17], v[14:15]
	s_nop 0
	v_cvt_pk_bf16_f32 v13, v14, v15
	v_mul_f32_e32 v14, 0xbfb8aa3b, v8
	v_mul_f32_e32 v15, 0xbfb8aa3b, v9
	v_exp_f32_e32 v14, v14
	v_exp_f32_e32 v15, v15
	v_add_f32_e32 v14, 1.0, v14
	v_add_f32_e32 v15, 1.0, v15
	v_rcp_f32_e32 v14, v14
	v_rcp_f32_e32 v15, v15
	s_nop 0
	v_pk_mul_f32 v[8:9], v[8:9], v[14:15]
	s_nop 0
	v_pk_mul_f32 v[4:5], v[8:9], v[4:5]
	s_nop 0
	v_cvt_pk_bf16_f32 v14, v4, v5
	v_mul_f32_e32 v4, 0xbfb8aa3b, v10
	v_mul_f32_e32 v5, 0xbfb8aa3b, v11
	v_exp_f32_e32 v4, v4
	v_exp_f32_e32 v5, v5
	v_add_f32_e32 v4, 1.0, v4
	v_add_f32_e32 v5, 1.0, v5
	v_rcp_f32_e32 v4, v4
	v_rcp_f32_e32 v5, v5
	s_nop 0
	v_pk_mul_f32 v[4:5], v[10:11], v[4:5]
	s_nop 0
	v_pk_mul_f32 v[4:5], v[4:5], v[6:7]
	s_nop 0
	v_cvt_pk_bf16_f32 v15, v4, v5
	global_store_dwordx4 v[20:21], v[12:15], off
	s_cbranch_vccz .LBB0_892
	s_waitcnt vmcnt(0)
	s_cmpk_gt_u32 s2, 0xff
	s_cbranch_scc1 .LBB0_903
	s_barrier
